# attention: both cross-lane reduction steps use v_permlane16_swap / v_permlane32_swap (no LDS bpermute left in the softmax)
# baseline (speedup 1.0000x reference)
; DI int otid() { int t = threadIdx.x & 255; asm volatile("" : "+v"(t)); return t; }
; template <int NKB>
; DI void attn_unit(const Params& p, int l, int mode, int grp, int head, int r0, int dil, int i0, int sub_len, int W, h16* lds) {
;     ...
;   h16* Qi = lds; h16* Ki = lds + 64 * LDH; h16* Vt = lds + 128 * LDH; h16* Pi = lds + 192 * LDH;
;   const int tid = otid(), lane = tid & 63, w = tid >> 6, r = lane & 15, q = lane >> 4;
;   const int lrow = tid >> 2, seg = tid & 3;
;   int qcol, kcol, vcol;
;   if (mode == 0) { qcol = 1024 + grp * 256 + head * 64; kcol = 1792 + grp * 256 + head * 64; vcol = 2560 + grp * 256 + head * 64; }
;   else { qcol = 4352 + head * 64; kcol = 4864 + (head >> 2) * 64; vcol = 4992 + (head >> 2) * 64; }
;   __syncthreads();
;   {
;     const size_t pos = (size_t)r0 + (size_t)dil * (i0 + lrow);
;     const h16* g = P + pos * NSM + qcol + 16 * seg;
;     img_store_nat(Qi, lrow, seg, *(const u4v*)g, *(const u4v*)(g + 8));
;   }
;   float mrow[4], lsum[4];
;   f4v O[4];
;   float m_init = -1e30f, l_init = 0.f;
;   if (mode == 1) { m_init = p.d_sink[l * 8 + head]; l_init = 1.f; }
; #pragma unroll
;   for (int i = 0; i < 4; ++i) { mrow[i] = m_init; lsum[i] = l_init; O[i] = (f4v){0.f, 0.f, 0.f, 0.f}; }
;   u4v pk0, pk1, pv0, pv1;
;     ...
;   ATT_PREFETCH(0);
; DI void phase_m2(const Params& p, int l, int bid, int nb, h16* lds) {
;     ...
;     v -= 2048;
;     const int grp = v >> 10, x = v & 1023, head = x & 3, tl = x >> 2;
;     const int dil = (grp == 0) ? 1 : (grp == 1) ? 4 : 16;
;     const int sub = SEQ / dil, tps = sub >> 6;
;     const int res = tl / tps, ti = tl % tps;
;     attn_unit<3>(p, l, 0, grp, head, res, dil, ti * 64, sub, 64, lds);
.LBB0_897:
	s_movk_i32 s2, 0x14a8
	v_cmp_gt_i32_e32 vcc, s2, v1
	s_and_saveexec_b64 s[2:3], vcc
	s_xor_b64 s[84:85], exec, s[2:3]
	s_cbranch_execz .LBB0_960
	v_cmp_lt_i32_e32 vcc, 31, v1
	s_and_saveexec_b64 s[2:3], vcc
	s_xor_b64 s[86:87], exec, s[2:3]
	s_cbranch_execz .LBB0_953
	s_movk_i32 s2, 0xa7
	v_cmp_lt_u32_e32 vcc, s2, v1
	s_and_saveexec_b64 s[2:3], vcc
	s_xor_b64 s[88:89], exec, s[2:3]
	s_cbranch_execz .LBB0_915
	s_movk_i32 s2, 0x8a7
	v_cmp_lt_u32_e32 vcc, s2, v1
	s_and_saveexec_b64 s[2:3], vcc
	s_xor_b64 s[34:35], exec, s[2:3]
	s_cbranch_execz .LBB0_910
	v_readfirstlane_b32 s36, v1
	v_readfirstlane_b32 s58, v182
	s_lshr_b32 s58, s58, 6
	s_sub_u32 s51, s36, 0x8a8
	s_and_b32 s56, s51, 15
	s_sub_u32 s56, s56, 8
	s_and_b32 s56, s56, 15
	s_lshr_b32 s56, s56, 1
	s_lshr_b32 s57, s51, 4
	s_lshl_b32 s57, s57, 1
	s_and_b32 s59, s51, 1
	s_or_b32 s57, s57, s59
	s_mul_i32 s59, s57, 0xaaab
	s_lshr_b32 s59, s59, 19
	s_mul_i32 s62, s59, 12
	s_sub_u32 s62, s57, s62
	s_lshr_b32 s61, s62, 2
	s_and_b32 s37, s62, 3
	s_lshl_b32 s62, s56, 5
	s_add_u32 s62, s62, s59
	s_lshl_b32 s63, s61, 1
	s_lshl_b32 s60, 1, s63
	s_movk_i32 s39, 0x2800
	s_lshl_b32 s39, s39, s63
	s_movk_i32 s41, 0x4000
	s_lshr_b32 s41, s41, s63
	s_sub_u32 s51, 8, s63
	s_lshr_b32 s40, s62, s51
	s_movk_i32 s51, 0x100
	s_lshr_b32 s51, s51, s63
	s_sub_u32 s51, s51, 1
	s_and_b32 s38, s62, s51
	s_lshl_b32 s38, s38, 6
	s_lshl_b32 s51, s61, 9
	s_lshl_b32 s56, s37, 7
	s_add_u32 s51, s51, s56
	s_add_u32 s53, s51, 0x800
	s_add_u32 s54, s51, 0xe00
	s_add_u32 s55, s51, 0x1400
	v_and_b32_e32 v179, 63, v182
	v_and_b32_e32 v200, 15, v179
	v_lshrrev_b32_e32 v201, 4, v179
	v_lshlrev_b32_e32 v202, 4, v201
	v_mad_u32_u24 v2, v200, s39, v202
	v_add_u32_e32 v203, 16, v200
	v_mad_u32_u24 v3, v203, s39, v202
	v_add_u32_e32 v203, 32, v200
	v_mad_u32_u24 v4, v203, s39, v202
	v_add_u32_e32 v203, 48, v200
	v_mad_u32_u24 v5, v203, s39, v202
	s_lshl_b32 s51, s58, 4
	v_add_u32_e32 v203, s51, v200
	v_mad_u32_u24 v248, v203, s39, v202
	v_lshlrev_b32_e32 v160, 2, v201
	v_sub_u32_e32 v160, v160, v203
	s_lshl_b32 s51, s60, 9
	v_mul_u32_u24_e32 v249, s51, v203
	s_lshl_b32 s51, s60, 5
	v_mul_u32_u24_e32 v203, s51, v203
	v_lshl_add_u32 v249, v201, 3, v249
	v_lshrrev_b32_e32 v203, 3, v179
	s_lshl_b32 s51, s58, 4
	v_add_u32_e32 v203, s51, v203
	v_and_b32_e32 v202, 7, v179
	v_lshlrev_b32_e32 v202, 4, v202
	v_mad_u32_u24 v6, v203, s39, v202
	v_add_u32_e32 v200, 8, v203
	v_mad_u32_u24 v7, v200, s39, v202
	s_movk_i32 s57, 0x90
	v_mad_u32_u24 v158, v203, s57, v183
	v_add_u32_e32 v158, v158, v202
	v_and_b32_e32 v200, 15, v179
	v_mad_u32_u24 v8, v200, s57, v183
	v_lshl_add_u32 v8, v201, 4, v8
	v_lshrrev_b32_e32 v203, 2, v179
	v_mad_u32_u24 v159, v203, s57, v183
	v_and_b32_e32 v203, 3, v179
	v_lshl_add_u32 v159, v203, 3, v159
	v_add_u32_e32 v159, 0x2400, v159
	v_xor_b32_e32 v174, 16, v179
	v_lshlrev_b32_e32 v174, 2, v174
	v_xor_b32_e32 v175, 32, v179
	v_lshlrev_b32_e32 v175, 2, v175
	s_mul_i32 s51, s60, s38
	s_add_u32 s51, s51, s40
	s_mul_i32 s56, s51, 0x2800
	s_add_u32 s56, s56, s53
	s_add_u32 s42, s0, s56
	s_addc_u32 s43, s1, 0
	global_load_dwordx4 v[10:13], v248, s[42:43]
	global_load_dwordx4 v[14:17], v248, s[42:43] offset:64
	v_readlane_b32 s48, v254, 32
	v_readlane_b32 s49, v254, 33
	v_readlane_b32 s16, v254, 34
	v_readlane_b32 s17, v254, 35
	s_lshl_b32 s56, s61, 14
	s_add_u32 s56, s56, s51
	s_lshl_b32 s57, s56, 9
	s_lshl_b32 s59, s37, 7
	s_add_u32 s57, s57, s59
	s_add_u32 s48, s48, s57
	s_addc_u32 s49, s49, 0
	s_lshl_b32 s57, s56, 5
	s_lshl_b32 s59, s37, 3
	s_add_u32 s57, s57, s59
	s_add_u32 s16, s16, s57
	s_addc_u32 s17, s17, 0
	v_mov_b32_e32 v176, 0xf149f2ca
	v_mov_b32_e32 v177, 0
	v_mov_b32_e32 v138, 0
	v_mov_b32_e32 v139, 0
	v_mov_b32_e32 v140, 0
	v_mov_b32_e32 v141, 0
	v_mov_b32_e32 v142, 0
	v_mov_b32_e32 v143, 0
	v_mov_b32_e32 v144, 0
	v_mov_b32_e32 v145, 0
	v_mov_b32_e32 v146, 0
	v_mov_b32_e32 v147, 0
	v_mov_b32_e32 v148, 0
	v_mov_b32_e32 v149, 0
	v_mov_b32_e32 v150, 0
	v_mov_b32_e32 v151, 0
	v_mov_b32_e32 v152, 0
	v_mov_b32_e32 v153, 0
	s_sub_u32 s50, s38, 64
	s_cmp_ge_i32 s50, 0
	s_cselect_b32 s56, 1, 0
	s_cmp_lt_i32 s50, s41
	s_cselect_b32 s57, 1, 0
	s_and_b32 s2, s56, s57
	s_cmp_eq_u32 s2, 1
	s_cselect_b32 s50, s50, s38
	s_mul_i32 s50, s50, s60
	s_add_u32 s50, s50, s40
	s_mul_i32 s50, s50, 0x2800
	s_add_u32 s56, s50, s54
	s_add_u32 s44, s0, s56
	s_addc_u32 s45, s1, 0
	s_add_u32 s56, s50, s55
	s_add_u32 s46, s0, s56
	s_addc_u32 s47, s1, 0
	global_load_dwordx4 v[50:53], v6, s[44:45]
	global_load_dwordx4 v[54:57], v7, s[44:45]
	global_load_dwordx4 v[58:61], v6, s[46:47]
	global_load_dwordx4 v[62:65], v7, s[46:47]
	s_add_u32 s50, s38, 0
	s_cmp_ge_i32 s50, 0
	s_cselect_b32 s56, 1, 0
	s_cmp_lt_i32 s50, s41
	s_cselect_b32 s57, 1, 0
	s_and_b32 s3, s56, s57
	s_cmp_eq_u32 s3, 1
	s_cselect_b32 s50, s50, s38
	s_mul_i32 s50, s50, s60
	s_add_u32 s50, s50, s40
	s_mul_i32 s50, s50, 0x2800
	s_add_u32 s56, s50, s54
	s_add_u32 s44, s0, s56
	s_addc_u32 s45, s1, 0
	s_add_u32 s56, s50, s55
	s_add_u32 s46, s0, s56
	s_addc_u32 s47, s1, 0
	global_load_dwordx4 v[66:69], v6, s[44:45]
	global_load_dwordx4 v[70:73], v7, s[44:45]
	global_load_dwordx4 v[74:77], v6, s[46:47]
	global_load_dwordx4 v[78:81], v7, s[46:47]
	s_waitcnt vmcnt(4)
	ds_write_b128 v158, v[50:53] offset:0
	ds_write_b128 v158, v[54:57] offset:1152
	ds_write_b128 v158, v[58:61] offset:9216
	ds_write_b128 v158, v[62:65] offset:10368
	s_waitcnt lgkmcnt(0)
	s_barrier
; DI float grp16_max(float v) { v = fmaxf(v, __shfl_xor(v, 1)); v = fmaxf(v, __shfl_xor(v, 2)); v = fmaxf(v, __shfl_xor(v, 4)); v = fmaxf(v, __shfl_xor(v, 8)); return v; }
; template <int NKB>
; DI void attn_unit(const Params& p, int l, int mode, int grp, int head, int r0, int dil, int i0, int sub_len, int W, h16* lds) {
;     ...
;   for (int kb = 0; kb < NKB; ++kb) {
;     const int j0 = i0 - W + 64 * kb;
;     const bool inr = (j0 >= 0) && (j0 < sub_len);
;     __syncthreads();
;     img_store_nat(Ki, lrow, seg, pk0, pk1);
;     img_store_T(Vt, lrow, seg, pv0, pv1);
;     __syncthreads();
;     if (kb + 1 < NKB) ATT_PREFETCH(kb + 1);
;     f4v S[4];
; #pragma unroll
;     for (int i = 0; i < 4; ++i) S[i] = (f4v){0.f, 0.f, 0.f, 0.f};
;     mm64(Qi, Ki, S, w, lane);
;     float mx[4], al[4], rsum[4];
;     bool vm[4][4];
; #pragma unroll
;     for (int rg = 0; rg < 4; ++rg) {
;       const int row = 16 * w + 4 * q + rg;
;       float m_ = -1e30f;
; #pragma unroll
;       for (int nt = 0; nt < 4; ++nt) {
;         const int key = 16 * nt + r;
;         const int delta = row - key + W - 64 * kb;
;         const bool ok = inr && (delta >= -W) && (delta <= W);
;         vm[nt][rg] = ok;
;         float s = S[nt][rg] * 0.125f;
;         S[nt][rg] = s;
;         if (ok) m_ = fmaxf(m_, s);
;       }
;       mx[rg] = grp16_max(m_);
;     }
; #pragma unroll
;     for (int rg = 0; rg < 4; ++rg) {
;       const float mn = fmaxf(mrow[rg], mx[rg]);
;       al[rg] = __expf(mrow[rg] - mn);
	s_add_u32 s50, s38, 64
	s_cmp_ge_i32 s50, 0
	s_cselect_b32 s56, 1, 0
	s_cmp_lt_i32 s50, s41
	s_cselect_b32 s57, 1, 0
	s_and_b32 s4, s56, s57
	s_cmp_eq_u32 s4, 1
	s_cselect_b32 s50, s50, s38
	s_mul_i32 s50, s50, s60
	s_add_u32 s50, s50, s40
	s_mul_i32 s50, s50, 0x2800
	s_add_u32 s56, s50, s54
	s_add_u32 s44, s0, s56
	s_addc_u32 s45, s1, 0
	s_add_u32 s56, s50, s55
	s_add_u32 s46, s0, s56
	s_addc_u32 s47, s1, 0
	global_load_dwordx4 v[50:53], v6, s[44:45]
	global_load_dwordx4 v[54:57], v7, s[44:45]
	global_load_dwordx4 v[58:61], v6, s[46:47]
	global_load_dwordx4 v[62:65], v7, s[46:47]
	s_cmp_eq_u32 s2, 1
	s_cbranch_scc0 .Lat0_kb0_end
	ds_read_b128 v[18:21], v8 offset:0
	ds_read_b128 v[22:25], v8 offset:64
	ds_read_b128 v[26:29], v8 offset:2304
	ds_read_b128 v[30:33], v8 offset:2368
	ds_read_b128 v[34:37], v8 offset:4608
	ds_read_b128 v[38:41], v8 offset:4672
	ds_read_b128 v[42:45], v8 offset:6912
	ds_read_b128 v[46:49], v8 offset:6976
	ds_read_b64_tr_b16 v[216:217], v159
	ds_read_b64_tr_b16 v[218:219], v159 offset:2304
	ds_read_b64_tr_b16 v[220:221], v159 offset:4608
	ds_read_b64_tr_b16 v[222:223], v159 offset:6912
	ds_read_b64_tr_b16 v[224:225], v159 offset:32
	ds_read_b64_tr_b16 v[226:227], v159 offset:2336
	ds_read_b64_tr_b16 v[228:229], v159 offset:4640
	ds_read_b64_tr_b16 v[230:231], v159 offset:6944
	ds_read_b64_tr_b16 v[232:233], v159 offset:64
	ds_read_b64_tr_b16 v[234:235], v159 offset:2368
	ds_read_b64_tr_b16 v[236:237], v159 offset:4672
	ds_read_b64_tr_b16 v[238:239], v159 offset:6976
	ds_read_b64_tr_b16 v[240:241], v159 offset:96
	ds_read_b64_tr_b16 v[242:243], v159 offset:2400
	ds_read_b64_tr_b16 v[244:245], v159 offset:4704
	ds_read_b64_tr_b16 v[246:247], v159 offset:7008
	s_waitcnt lgkmcnt(15)
	v_mfma_f32_16x16x32_f16 v[114:117], v[18:21], v[10:13], 0
	v_mfma_f32_16x16x32_f16 v[118:121], v[26:29], v[10:13], 0
	v_mfma_f32_16x16x32_f16 v[122:125], v[34:37], v[10:13], 0
	v_mfma_f32_16x16x32_f16 v[126:129], v[42:45], v[10:13], 0
	v_mfma_f32_16x16x32_f16 v[114:117], v[22:25], v[14:17], v[114:117]
	v_mfma_f32_16x16x32_f16 v[118:121], v[30:33], v[14:17], v[118:121]
	v_mfma_f32_16x16x32_f16 v[122:125], v[38:41], v[14:17], v[122:125]
	v_mfma_f32_16x16x32_f16 v[126:129], v[46:49], v[14:17], v[126:129]
	s_nop 7
	s_nop 7
	v_mul_f32_e32 v114, 0x3e000000, v114
	v_mul_f32_e32 v115, 0x3e000000, v115
	v_mul_f32_e32 v116, 0x3e000000, v116
	v_mul_f32_e32 v117, 0x3e000000, v117
	v_mul_f32_e32 v118, 0x3e000000, v118
	v_mul_f32_e32 v119, 0x3e000000, v119
	v_mul_f32_e32 v120, 0x3e000000, v120
	v_mul_f32_e32 v121, 0x3e000000, v121
	v_mul_f32_e32 v122, 0x3e000000, v122
	v_mul_f32_e32 v123, 0x3e000000, v123
	v_mul_f32_e32 v124, 0x3e000000, v124
	v_mul_f32_e32 v125, 0x3e000000, v125
	v_mul_f32_e32 v126, 0x3e000000, v126
	v_mul_f32_e32 v127, 0x3e000000, v127
	v_mul_f32_e32 v128, 0x3e000000, v128
	v_mul_f32_e32 v129, 0x3e000000, v129
	v_mov_b32_e32 v200, 0xf149f2ca
	v_cmp_le_i32_e32 vcc, 0, v160
	v_cndmask_b32_e32 v114, v200, v114, vcc
	v_cmp_le_i32_e32 vcc, -1, v160
	v_cndmask_b32_e32 v115, v200, v115, vcc
	v_cmp_le_i32_e32 vcc, -2, v160
	v_cndmask_b32_e32 v116, v200, v116, vcc
	v_cmp_le_i32_e32 vcc, -3, v160
	v_cndmask_b32_e32 v117, v200, v117, vcc
	v_cmp_le_i32_e32 vcc, -16, v160
	v_cndmask_b32_e32 v118, v200, v118, vcc
	v_cmp_le_i32_e32 vcc, -17, v160
	v_cndmask_b32_e32 v119, v200, v119, vcc
	v_cmp_le_i32_e32 vcc, -18, v160
	v_cndmask_b32_e32 v120, v200, v120, vcc
	v_cmp_le_i32_e32 vcc, -19, v160
	v_cndmask_b32_e32 v121, v200, v121, vcc
	v_cmp_le_i32_e32 vcc, -32, v160
	v_cndmask_b32_e32 v122, v200, v122, vcc
	v_cmp_le_i32_e32 vcc, -33, v160
	v_cndmask_b32_e32 v123, v200, v123, vcc
	v_cmp_le_i32_e32 vcc, -34, v160
	v_cndmask_b32_e32 v124, v200, v124, vcc
	v_cmp_le_i32_e32 vcc, -35, v160
	v_cndmask_b32_e32 v125, v200, v125, vcc
	v_cmp_le_i32_e32 vcc, -48, v160
	v_cndmask_b32_e32 v126, v200, v126, vcc
	v_cmp_le_i32_e32 vcc, -49, v160
	v_cndmask_b32_e32 v127, v200, v127, vcc
	v_cmp_le_i32_e32 vcc, -50, v160
	v_cndmask_b32_e32 v128, v200, v128, vcc
	v_cmp_le_i32_e32 vcc, -51, v160
	v_cndmask_b32_e32 v129, v200, v129, vcc
	v_max3_f32 v179, v114, v115, v116
	v_max3_f32 v179, v179, v117, v118
	v_max3_f32 v179, v179, v119, v120
	v_max3_f32 v179, v179, v121, v122
	v_max3_f32 v179, v179, v123, v124
	v_max3_f32 v179, v179, v125, v126
	v_max3_f32 v179, v179, v127, v128
	v_max_f32_e32 v179, v179, v129
	v_mov_b32_e32 v201, v179
	s_nop 1
	v_permlane16_swap_b32 v201, v179
	s_nop 1
	v_max_f32_e32 v179, v179, v201
	v_mov_b32_e32 v201, v179
	s_nop 1
	v_permlane32_swap_b32 v201, v179
	s_nop 1
	v_max3_f32 v179, v179, v201, v176
	v_sub_f32_e32 v178, v176, v179
	v_mul_f32_e32 v178, 0x3fb8aa3b, v178
	v_exp_f32_e32 v178, v178
	v_mov_b32_e32 v176, v179
	v_mul_f32_e32 v202, 0xbfb8aa3b, v179
	v_mov_b32_e32 v203, 0x3fb8aa3b
	v_fma_f32 v114, v114, v203, v202
	v_fma_f32 v115, v115, v203, v202
	v_fma_f32 v116, v116, v203, v202
	v_fma_f32 v117, v117, v203, v202
	v_fma_f32 v118, v118, v203, v202
	v_fma_f32 v119, v119, v203, v202
	v_fma_f32 v120, v120, v203, v202
	v_fma_f32 v121, v121, v203, v202
	v_fma_f32 v122, v122, v203, v202
	v_fma_f32 v123, v123, v203, v202
	v_fma_f32 v124, v124, v203, v202
	v_fma_f32 v125, v125, v203, v202
	v_fma_f32 v126, v126, v203, v202
	v_fma_f32 v127, v127, v203, v202
	v_fma_f32 v128, v128, v203, v202
	v_fma_f32 v129, v129, v203, v202
	v_exp_f32_e32 v114, v114
	v_exp_f32_e32 v115, v115
	v_exp_f32_e32 v116, v116
	v_exp_f32_e32 v117, v117
	v_exp_f32_e32 v118, v118
	v_exp_f32_e32 v119, v119
	v_exp_f32_e32 v120, v120
	v_exp_f32_e32 v121, v121
	v_exp_f32_e32 v122, v122
	v_exp_f32_e32 v123, v123
	v_exp_f32_e32 v124, v124
	v_exp_f32_e32 v125, v125
; DI float grp16_sum(float v) { v += __shfl_xor(v, 1); v += __shfl_xor(v, 2); v += __shfl_xor(v, 4); v += __shfl_xor(v, 8); return v; }
; DI float grp16_max(float v) { v = fmaxf(v, __shfl_xor(v, 1)); v = fmaxf(v, __shfl_xor(v, 2)); v = fmaxf(v, __shfl_xor(v, 4)); v = fmaxf(v, __shfl_xor(v, 8)); return v; }
; template <int NKB>
; DI void attn_unit(const Params& p, int l, int mode, int grp, int head, int r0, int dil, int i0, int sub_len, int W, h16* lds) {
;     ...
;   for (int kb = 0; kb < NKB; ++kb) {
;     const int j0 = i0 - W + 64 * kb;
;     const bool inr = (j0 >= 0) && (j0 < sub_len);
;     __syncthreads();
;     img_store_nat(Ki, lrow, seg, pk0, pk1);
;     img_store_T(Vt, lrow, seg, pv0, pv1);
;     __syncthreads();
;     if (kb + 1 < NKB) ATT_PREFETCH(kb + 1);
;     f4v S[4];
; #pragma unroll
;     for (int i = 0; i < 4; ++i) S[i] = (f4v){0.f, 0.f, 0.f, 0.f};
;     mm64(Qi, Ki, S, w, lane);
;     float mx[4], al[4], rsum[4];
;     bool vm[4][4];
; #pragma unroll
;     for (int rg = 0; rg < 4; ++rg) {
;       const int row = 16 * w + 4 * q + rg;
;       float m_ = -1e30f;
; #pragma unroll
;       for (int nt = 0; nt < 4; ++nt) {
;         const int key = 16 * nt + r;
;         const int delta = row - key + W - 64 * kb;
;         const bool ok = inr && (delta >= -W) && (delta <= W);
;         vm[nt][rg] = ok;
;         float s = S[nt][rg] * 0.125f;
;         S[nt][rg] = s;
;         if (ok) m_ = fmaxf(m_, s);
;       }
;       mx[rg] = grp16_max(m_);
;     }
; #pragma unroll
;     for (int rg = 0; rg < 4; ++rg) {
;       const float mn = fmaxf(mrow[rg], mx[rg]);
;       al[rg] = __expf(mrow[rg] - mn);
;       mrow[rg] = mn;
;       float rs_ = 0.f;
; #pragma unroll
;       for (int nt = 0; nt < 4; ++nt) {
;         float pv = vm[nt][rg] ? __expf(S[nt][rg] - mn) : 0.f;
;         rs_ += pv;
;         Pi[(16 * w + 4 * q + rg) * LDH + 16 * nt + r] = (h16)pv;
;       }
;       rsum[rg] = grp16_sum(rs_);
;       lsum[rg] = lsum[rg] * al[rg] + rsum[rg];
;     }
; #pragma unroll
;     for (int et = 0; et < 4; ++et)
; #pragma unroll
;       for (int rg = 0; rg < 4; ++rg) O[et][rg] *= al[rg];
;     __syncthreads();
;     mm64(Pi, Vt, O, w, lane);
;   }
	v_exp_f32_e32 v126, v126
	v_exp_f32_e32 v127, v127
	v_exp_f32_e32 v128, v128
	v_exp_f32_e32 v129, v129
	s_nop 0
	v_fma_f32 v177, v177, v178, v114
	v_add_f32_e32 v177, v177, v115
	v_add_f32_e32 v177, v177, v116
	v_add_f32_e32 v177, v177, v117
	v_add_f32_e32 v177, v177, v118
	v_add_f32_e32 v177, v177, v119
	v_add_f32_e32 v177, v177, v120
	v_add_f32_e32 v177, v177, v121
	v_add_f32_e32 v177, v177, v122
	v_add_f32_e32 v177, v177, v123
	v_add_f32_e32 v177, v177, v124
	v_add_f32_e32 v177, v177, v125
	v_add_f32_e32 v177, v177, v126
	v_add_f32_e32 v177, v177, v127
	v_add_f32_e32 v177, v177, v128
	v_add_f32_e32 v177, v177, v129
	v_cvt_pk_f16_f32 v130, v114, v115
	v_cvt_pk_f16_f32 v131, v116, v117
	v_cvt_pk_f16_f32 v132, v118, v119
	v_cvt_pk_f16_f32 v133, v120, v121
	v_cvt_pk_f16_f32 v134, v122, v123
	v_cvt_pk_f16_f32 v135, v124, v125
	v_cvt_pk_f16_f32 v136, v126, v127
	v_cvt_pk_f16_f32 v137, v128, v129
	v_pk_mul_f32 v[138:139], v[138:139], v[178:179] op_sel_hi:[1,0]
	v_pk_mul_f32 v[140:141], v[140:141], v[178:179] op_sel_hi:[1,0]
	v_pk_mul_f32 v[142:143], v[142:143], v[178:179] op_sel_hi:[1,0]
	v_pk_mul_f32 v[144:145], v[144:145], v[178:179] op_sel_hi:[1,0]
	v_pk_mul_f32 v[146:147], v[146:147], v[178:179] op_sel_hi:[1,0]
	v_pk_mul_f32 v[148:149], v[148:149], v[178:179] op_sel_hi:[1,0]
	v_pk_mul_f32 v[150:151], v[150:151], v[178:179] op_sel_hi:[1,0]
	v_pk_mul_f32 v[152:153], v[152:153], v[178:179] op_sel_hi:[1,0]
	s_waitcnt lgkmcnt(0)
	s_nop 1
	v_mfma_f32_16x16x32_f16 v[138:141], v[216:219], v[130:133], v[138:141]
	v_mfma_f32_16x16x32_f16 v[142:145], v[224:227], v[130:133], v[142:145]
	v_mfma_f32_16x16x32_f16 v[146:149], v[232:235], v[130:133], v[146:149]
	v_mfma_f32_16x16x32_f16 v[150:153], v[240:243], v[130:133], v[150:153]
	v_mfma_f32_16x16x32_f16 v[138:141], v[220:223], v[134:137], v[138:141]
	v_mfma_f32_16x16x32_f16 v[142:145], v[228:231], v[134:137], v[142:145]
	v_mfma_f32_16x16x32_f16 v[146:149], v[236:239], v[134:137], v[146:149]
	v_mfma_f32_16x16x32_f16 v[150:153], v[244:247], v[134:137], v[150:153]
.Lat0_kb0_end:
	s_waitcnt vmcnt(4)
	ds_write_b128 v158, v[66:69] offset:18432
	ds_write_b128 v158, v[70:73] offset:19584
	ds_write_b128 v158, v[74:77] offset:27648
	ds_write_b128 v158, v[78:81] offset:28800
	s_waitcnt lgkmcnt(0)
	s_barrier
	s_cmp_eq_u32 s3, 1
	s_cbranch_scc0 .Lat0_kb1_end
	ds_read_b128 v[18:21], v8 offset:18432
	ds_read_b128 v[22:25], v8 offset:18496
	ds_read_b128 v[26:29], v8 offset:20736
	ds_read_b128 v[30:33], v8 offset:20800
	ds_read_b128 v[34:37], v8 offset:23040
	ds_read_b128 v[38:41], v8 offset:23104
	ds_read_b128 v[42:45], v8 offset:25344
	ds_read_b128 v[46:49], v8 offset:25408
	ds_read_b64_tr_b16 v[216:217], v159 offset:18432
	ds_read_b64_tr_b16 v[218:219], v159 offset:20736
	ds_read_b64_tr_b16 v[220:221], v159 offset:23040
	ds_read_b64_tr_b16 v[222:223], v159 offset:25344
	ds_read_b64_tr_b16 v[224:225], v159 offset:18464
	ds_read_b64_tr_b16 v[226:227], v159 offset:20768
	ds_read_b64_tr_b16 v[228:229], v159 offset:23072
	ds_read_b64_tr_b16 v[230:231], v159 offset:25376
	ds_read_b64_tr_b16 v[232:233], v159 offset:18496
	ds_read_b64_tr_b16 v[234:235], v159 offset:20800
	ds_read_b64_tr_b16 v[236:237], v159 offset:23104
	ds_read_b64_tr_b16 v[238:239], v159 offset:25408
	ds_read_b64_tr_b16 v[240:241], v159 offset:18528
	ds_read_b64_tr_b16 v[242:243], v159 offset:20832
	ds_read_b64_tr_b16 v[244:245], v159 offset:23136
	ds_read_b64_tr_b16 v[246:247], v159 offset:25440
	s_waitcnt lgkmcnt(15)
	v_mfma_f32_16x16x32_f16 v[114:117], v[18:21], v[10:13], 0
	v_mfma_f32_16x16x32_f16 v[118:121], v[26:29], v[10:13], 0
	v_mfma_f32_16x16x32_f16 v[122:125], v[34:37], v[10:13], 0
	v_mfma_f32_16x16x32_f16 v[126:129], v[42:45], v[10:13], 0
	v_mfma_f32_16x16x32_f16 v[114:117], v[22:25], v[14:17], v[114:117]
	v_mfma_f32_16x16x32_f16 v[118:121], v[30:33], v[14:17], v[118:121]
	v_mfma_f32_16x16x32_f16 v[122:125], v[38:41], v[14:17], v[122:125]
	v_mfma_f32_16x16x32_f16 v[126:129], v[46:49], v[14:17], v[126:129]
	s_nop 7
	s_nop 7
	v_mul_f32_e32 v114, 0x3e000000, v114
	v_mul_f32_e32 v115, 0x3e000000, v115
	v_mul_f32_e32 v116, 0x3e000000, v116
	v_mul_f32_e32 v117, 0x3e000000, v117
	v_mul_f32_e32 v118, 0x3e000000, v118
	v_mul_f32_e32 v119, 0x3e000000, v119
	v_mul_f32_e32 v120, 0x3e000000, v120
	v_mul_f32_e32 v121, 0x3e000000, v121
	v_mul_f32_e32 v122, 0x3e000000, v122
	v_mul_f32_e32 v123, 0x3e000000, v123
	v_mul_f32_e32 v124, 0x3e000000, v124
	v_mul_f32_e32 v125, 0x3e000000, v125
	v_mul_f32_e32 v126, 0x3e000000, v126
	v_mul_f32_e32 v127, 0x3e000000, v127
	v_mul_f32_e32 v128, 0x3e000000, v128
	v_mul_f32_e32 v129, 0x3e000000, v129
	v_max3_f32 v179, v114, v115, v116
	v_max3_f32 v179, v179, v117, v118
	v_max3_f32 v179, v179, v119, v120
	v_max3_f32 v179, v179, v121, v122
	v_max3_f32 v179, v179, v123, v124
	v_max3_f32 v179, v179, v125, v126
	v_max3_f32 v179, v179, v127, v128
	v_max_f32_e32 v179, v179, v129
	v_mov_b32_e32 v201, v179
	s_nop 1
	v_permlane16_swap_b32 v201, v179
	s_nop 1
	v_max_f32_e32 v179, v179, v201
	v_mov_b32_e32 v201, v179
	s_nop 1
	v_permlane32_swap_b32 v201, v179
	s_nop 1
	v_max3_f32 v179, v179, v201, v176
	v_sub_f32_e32 v178, v176, v179
	v_mul_f32_e32 v178, 0x3fb8aa3b, v178
	v_exp_f32_e32 v178, v178
	v_mov_b32_e32 v176, v179
	v_mul_f32_e32 v202, 0xbfb8aa3b, v179
	v_mov_b32_e32 v203, 0x3fb8aa3b
	v_fma_f32 v114, v114, v203, v202
	v_fma_f32 v115, v115, v203, v202
	v_fma_f32 v116, v116, v203, v202
	v_fma_f32 v117, v117, v203, v202
	v_fma_f32 v118, v118, v203, v202
	v_fma_f32 v119, v119, v203, v202
	v_fma_f32 v120, v120, v203, v202
	v_fma_f32 v121, v121, v203, v202
	v_fma_f32 v122, v122, v203, v202
	v_fma_f32 v123, v123, v203, v202
; DI float grp16_sum(float v) { v += __shfl_xor(v, 1); v += __shfl_xor(v, 2); v += __shfl_xor(v, 4); v += __shfl_xor(v, 8); return v; }
; DI float grp16_max(float v) { v = fmaxf(v, __shfl_xor(v, 1)); v = fmaxf(v, __shfl_xor(v, 2)); v = fmaxf(v, __shfl_xor(v, 4)); v = fmaxf(v, __shfl_xor(v, 8)); return v; }
; template <int NKB>
; DI void attn_unit(const Params& p, int l, int mode, int grp, int head, int r0, int dil, int i0, int sub_len, int W, h16* lds) {
;     ...
;   for (int kb = 0; kb < NKB; ++kb) {
;     const int j0 = i0 - W + 64 * kb;
;     const bool inr = (j0 >= 0) && (j0 < sub_len);
;     __syncthreads();
;     img_store_nat(Ki, lrow, seg, pk0, pk1);
;     img_store_T(Vt, lrow, seg, pv0, pv1);
;     __syncthreads();
;     if (kb + 1 < NKB) ATT_PREFETCH(kb + 1);
;     f4v S[4];
; #pragma unroll
;     for (int i = 0; i < 4; ++i) S[i] = (f4v){0.f, 0.f, 0.f, 0.f};
;     mm64(Qi, Ki, S, w, lane);
;     float mx[4], al[4], rsum[4];
;     bool vm[4][4];
; #pragma unroll
;     for (int rg = 0; rg < 4; ++rg) {
;       const int row = 16 * w + 4 * q + rg;
;       float m_ = -1e30f;
; #pragma unroll
;       for (int nt = 0; nt < 4; ++nt) {
;         const int key = 16 * nt + r;
;         const int delta = row - key + W - 64 * kb;
;         const bool ok = inr && (delta >= -W) && (delta <= W);
;         vm[nt][rg] = ok;
;         float s = S[nt][rg] * 0.125f;
;         S[nt][rg] = s;
;         if (ok) m_ = fmaxf(m_, s);
;       }
;       mx[rg] = grp16_max(m_);
;     }
; #pragma unroll
;     for (int rg = 0; rg < 4; ++rg) {
;       const float mn = fmaxf(mrow[rg], mx[rg]);
;       al[rg] = __expf(mrow[rg] - mn);
;       mrow[rg] = mn;
;       float rs_ = 0.f;
; #pragma unroll
;       for (int nt = 0; nt < 4; ++nt) {
;         float pv = vm[nt][rg] ? __expf(S[nt][rg] - mn) : 0.f;
;         rs_ += pv;
;         Pi[(16 * w + 4 * q + rg) * LDH + 16 * nt + r] = (h16)pv;
;       }
;       rsum[rg] = grp16_sum(rs_);
;       lsum[rg] = lsum[rg] * al[rg] + rsum[rg];
;     }
; #pragma unroll
;     for (int et = 0; et < 4; ++et)
; #pragma unroll
;       for (int rg = 0; rg < 4; ++rg) O[et][rg] *= al[rg];
;     __syncthreads();
;     mm64(Pi, Vt, O, w, lane);
;   }
	v_fma_f32 v124, v124, v203, v202
	v_fma_f32 v125, v125, v203, v202
	v_fma_f32 v126, v126, v203, v202
	v_fma_f32 v127, v127, v203, v202
	v_fma_f32 v128, v128, v203, v202
	v_fma_f32 v129, v129, v203, v202
	v_exp_f32_e32 v114, v114
	v_exp_f32_e32 v115, v115
	v_exp_f32_e32 v116, v116
	v_exp_f32_e32 v117, v117
	v_exp_f32_e32 v118, v118
	v_exp_f32_e32 v119, v119
	v_exp_f32_e32 v120, v120
	v_exp_f32_e32 v121, v121
	v_exp_f32_e32 v122, v122
	v_exp_f32_e32 v123, v123
	v_exp_f32_e32 v124, v124
	v_exp_f32_e32 v125, v125
	v_exp_f32_e32 v126, v126
	v_exp_f32_e32 v127, v127
	v_exp_f32_e32 v128, v128
	v_exp_f32_e32 v129, v129
	s_nop 0
	v_fma_f32 v177, v177, v178, v114
	v_add_f32_e32 v177, v177, v115
	v_add_f32_e32 v177, v177, v116
	v_add_f32_e32 v177, v177, v117
	v_add_f32_e32 v177, v177, v118
	v_add_f32_e32 v177, v177, v119
	v_add_f32_e32 v177, v177, v120
	v_add_f32_e32 v177, v177, v121
	v_add_f32_e32 v177, v177, v122
	v_add_f32_e32 v177, v177, v123
	v_add_f32_e32 v177, v177, v124
	v_add_f32_e32 v177, v177, v125
	v_add_f32_e32 v177, v177, v126
	v_add_f32_e32 v177, v177, v127
	v_add_f32_e32 v177, v177, v128
	v_add_f32_e32 v177, v177, v129
	v_cvt_pk_f16_f32 v130, v114, v115
	v_cvt_pk_f16_f32 v131, v116, v117
	v_cvt_pk_f16_f32 v132, v118, v119
	v_cvt_pk_f16_f32 v133, v120, v121
	v_cvt_pk_f16_f32 v134, v122, v123
	v_cvt_pk_f16_f32 v135, v124, v125
	v_cvt_pk_f16_f32 v136, v126, v127
	v_cvt_pk_f16_f32 v137, v128, v129
	v_pk_mul_f32 v[138:139], v[138:139], v[178:179] op_sel_hi:[1,0]
	v_pk_mul_f32 v[140:141], v[140:141], v[178:179] op_sel_hi:[1,0]
	v_pk_mul_f32 v[142:143], v[142:143], v[178:179] op_sel_hi:[1,0]
	v_pk_mul_f32 v[144:145], v[144:145], v[178:179] op_sel_hi:[1,0]
	v_pk_mul_f32 v[146:147], v[146:147], v[178:179] op_sel_hi:[1,0]
	v_pk_mul_f32 v[148:149], v[148:149], v[178:179] op_sel_hi:[1,0]
	v_pk_mul_f32 v[150:151], v[150:151], v[178:179] op_sel_hi:[1,0]
	v_pk_mul_f32 v[152:153], v[152:153], v[178:179] op_sel_hi:[1,0]
	s_waitcnt lgkmcnt(0)
	s_nop 1
	v_mfma_f32_16x16x32_f16 v[138:141], v[216:219], v[130:133], v[138:141]
	v_mfma_f32_16x16x32_f16 v[142:145], v[224:227], v[130:133], v[142:145]
	v_mfma_f32_16x16x32_f16 v[146:149], v[232:235], v[130:133], v[146:149]
	v_mfma_f32_16x16x32_f16 v[150:153], v[240:243], v[130:133], v[150:153]
	v_mfma_f32_16x16x32_f16 v[138:141], v[220:223], v[134:137], v[138:141]
	v_mfma_f32_16x16x32_f16 v[142:145], v[228:231], v[134:137], v[142:145]
	v_mfma_f32_16x16x32_f16 v[146:149], v[236:239], v[134:137], v[146:149]
	v_mfma_f32_16x16x32_f16 v[150:153], v[244:247], v[134:137], v[150:153]
.Lat0_kb1_end:
	s_waitcnt vmcnt(0)
	ds_write_b128 v158, v[50:53] offset:36864
	ds_write_b128 v158, v[54:57] offset:38016
	ds_write_b128 v158, v[58:61] offset:46080
	ds_write_b128 v158, v[62:65] offset:47232
	s_waitcnt lgkmcnt(0)
	s_barrier
	s_cmp_eq_u32 s4, 1
	s_cbranch_scc0 .Lat0_kb2_end
	ds_read_b128 v[18:21], v8 offset:36864
	ds_read_b128 v[22:25], v8 offset:36928
	ds_read_b128 v[26:29], v8 offset:39168
	ds_read_b128 v[30:33], v8 offset:39232
	ds_read_b128 v[34:37], v8 offset:41472
	ds_read_b128 v[38:41], v8 offset:41536
	ds_read_b128 v[42:45], v8 offset:43776
	ds_read_b128 v[46:49], v8 offset:43840
	ds_read_b64_tr_b16 v[216:217], v159 offset:36864
	ds_read_b64_tr_b16 v[218:219], v159 offset:39168
	ds_read_b64_tr_b16 v[220:221], v159 offset:41472
	ds_read_b64_tr_b16 v[222:223], v159 offset:43776
	ds_read_b64_tr_b16 v[224:225], v159 offset:36896
	ds_read_b64_tr_b16 v[226:227], v159 offset:39200
	ds_read_b64_tr_b16 v[228:229], v159 offset:41504
	ds_read_b64_tr_b16 v[230:231], v159 offset:43808
	ds_read_b64_tr_b16 v[232:233], v159 offset:36928
	ds_read_b64_tr_b16 v[234:235], v159 offset:39232
	ds_read_b64_tr_b16 v[236:237], v159 offset:41536
	ds_read_b64_tr_b16 v[238:239], v159 offset:43840
	ds_read_b64_tr_b16 v[240:241], v159 offset:36960
	ds_read_b64_tr_b16 v[242:243], v159 offset:39264
	ds_read_b64_tr_b16 v[244:245], v159 offset:41568
	ds_read_b64_tr_b16 v[246:247], v159 offset:43872
	s_waitcnt lgkmcnt(15)
	v_mfma_f32_16x16x32_f16 v[114:117], v[18:21], v[10:13], 0
	v_mfma_f32_16x16x32_f16 v[118:121], v[26:29], v[10:13], 0
	v_mfma_f32_16x16x32_f16 v[122:125], v[34:37], v[10:13], 0
	v_mfma_f32_16x16x32_f16 v[126:129], v[42:45], v[10:13], 0
	v_mfma_f32_16x16x32_f16 v[114:117], v[22:25], v[14:17], v[114:117]
	v_mfma_f32_16x16x32_f16 v[118:121], v[30:33], v[14:17], v[118:121]
	v_mfma_f32_16x16x32_f16 v[122:125], v[38:41], v[14:17], v[122:125]
	v_mfma_f32_16x16x32_f16 v[126:129], v[46:49], v[14:17], v[126:129]
	s_nop 7
	s_nop 7
	v_mul_f32_e32 v114, 0x3e000000, v114
	v_mul_f32_e32 v115, 0x3e000000, v115
	v_mul_f32_e32 v116, 0x3e000000, v116
	v_mul_f32_e32 v117, 0x3e000000, v117
	v_mul_f32_e32 v118, 0x3e000000, v118
	v_mul_f32_e32 v119, 0x3e000000, v119
	v_mul_f32_e32 v120, 0x3e000000, v120
	v_mul_f32_e32 v121, 0x3e000000, v121
	v_mul_f32_e32 v122, 0x3e000000, v122
	v_mul_f32_e32 v123, 0x3e000000, v123
	v_mul_f32_e32 v124, 0x3e000000, v124
	v_mul_f32_e32 v125, 0x3e000000, v125
	v_mul_f32_e32 v126, 0x3e000000, v126
	v_mul_f32_e32 v127, 0x3e000000, v127
	v_mul_f32_e32 v128, 0x3e000000, v128
	v_mul_f32_e32 v129, 0x3e000000, v129
	v_mov_b32_e32 v200, 0xf149f2ca
	v_cmp_ge_i32_e32 vcc, 0, v160
	v_cndmask_b32_e32 v114, v200, v114, vcc
	v_cmp_ge_i32_e32 vcc, -1, v160
	v_cndmask_b32_e32 v115, v200, v115, vcc
	v_cmp_ge_i32_e32 vcc, -2, v160
	v_cndmask_b32_e32 v116, v200, v116, vcc
	v_cmp_ge_i32_e32 vcc, -3, v160
	v_cndmask_b32_e32 v117, v200, v117, vcc
	v_cmp_ge_i32_e32 vcc, -16, v160
	v_cndmask_b32_e32 v118, v200, v118, vcc
	v_cmp_ge_i32_e32 vcc, -17, v160
	v_cndmask_b32_e32 v119, v200, v119, vcc
	v_cmp_ge_i32_e32 vcc, -18, v160
; DI float grp16_sum(float v) { v += __shfl_xor(v, 1); v += __shfl_xor(v, 2); v += __shfl_xor(v, 4); v += __shfl_xor(v, 8); return v; }
; template <int NKB>
; DI void attn_unit(const Params& p, int l, int mode, int grp, int head, int r0, int dil, int i0, int sub_len, int W, h16* lds) {
;     ...
;     for (int rg = 0; rg < 4; ++rg) {
;       const float mn = fmaxf(mrow[rg], mx[rg]);
;       al[rg] = __expf(mrow[rg] - mn);
;       mrow[rg] = mn;
;       float rs_ = 0.f;
; #pragma unroll
;       for (int nt = 0; nt < 4; ++nt) {
;         float pv = vm[nt][rg] ? __expf(S[nt][rg] - mn) : 0.f;
;         rs_ += pv;
;         Pi[(16 * w + 4 * q + rg) * LDH + 16 * nt + r] = (h16)pv;
;       }
;       rsum[rg] = grp16_sum(rs_);
;       lsum[rg] = lsum[rg] * al[rg] + rsum[rg];
;     }
; #pragma unroll
;     for (int et = 0; et < 4; ++et)
; #pragma unroll
;       for (int rg = 0; rg < 4; ++rg) O[et][rg] *= al[rg];
;     __syncthreads();
;     mm64(Pi, Vt, O, w, lane);
;   }
; #pragma unroll
;   for (int rg = 0; rg < 4; ++rg) {
;     const int row = 16 * w + 4 * q + rg;
;     const size_t pos = (size_t)r0 + (size_t)dil * (i0 + row);
;     const float inv = 1.f / lsum[rg];
;     if (mode == 0) {
;       h16* ob = (h16*)(ws + OFF_OB) + ((size_t)grp * SEQ + pos) * 256 + head * 64;
; #pragma unroll
;       for (int et = 0; et < 4; ++et) ob[16 * et + r] = (h16)(O[et][rg] * inv);
;       if (r == 0) {
;         float* ml = (float*)(ws + OFF_MLB) + (((size_t)grp * SEQ + pos) * 4 + head) * 2;
;         ml[0] = mrow[rg]; ml[1] = lsum[rg];
;       }
	v_cndmask_b32_e32 v120, v200, v120, vcc
	v_cmp_ge_i32_e32 vcc, -19, v160
	v_cndmask_b32_e32 v121, v200, v121, vcc
	v_cmp_ge_i32_e32 vcc, -32, v160
	v_cndmask_b32_e32 v122, v200, v122, vcc
	v_cmp_ge_i32_e32 vcc, -33, v160
	v_cndmask_b32_e32 v123, v200, v123, vcc
	v_cmp_ge_i32_e32 vcc, -34, v160
	v_cndmask_b32_e32 v124, v200, v124, vcc
	v_cmp_ge_i32_e32 vcc, -35, v160
	v_cndmask_b32_e32 v125, v200, v125, vcc
	v_cmp_ge_i32_e32 vcc, -48, v160
	v_cndmask_b32_e32 v126, v200, v126, vcc
	v_cmp_ge_i32_e32 vcc, -49, v160
	v_cndmask_b32_e32 v127, v200, v127, vcc
	v_cmp_ge_i32_e32 vcc, -50, v160
	v_cndmask_b32_e32 v128, v200, v128, vcc
	v_cmp_ge_i32_e32 vcc, -51, v160
	v_cndmask_b32_e32 v129, v200, v129, vcc
	v_max3_f32 v179, v114, v115, v116
	v_max3_f32 v179, v179, v117, v118
	v_max3_f32 v179, v179, v119, v120
	v_max3_f32 v179, v179, v121, v122
	v_max3_f32 v179, v179, v123, v124
	v_max3_f32 v179, v179, v125, v126
	v_max3_f32 v179, v179, v127, v128
	v_max_f32_e32 v179, v179, v129
	v_mov_b32_e32 v201, v179
	s_nop 1
	v_permlane16_swap_b32 v201, v179
	s_nop 1
	v_max_f32_e32 v179, v179, v201
	v_mov_b32_e32 v201, v179
	s_nop 1
	v_permlane32_swap_b32 v201, v179
	s_nop 1
	v_max3_f32 v179, v179, v201, v176
	v_sub_f32_e32 v178, v176, v179
	v_mul_f32_e32 v178, 0x3fb8aa3b, v178
	v_exp_f32_e32 v178, v178
	v_mov_b32_e32 v176, v179
	v_mul_f32_e32 v202, 0xbfb8aa3b, v179
	v_mov_b32_e32 v203, 0x3fb8aa3b
	v_fma_f32 v114, v114, v203, v202
	v_fma_f32 v115, v115, v203, v202
	v_fma_f32 v116, v116, v203, v202
	v_fma_f32 v117, v117, v203, v202
	v_fma_f32 v118, v118, v203, v202
	v_fma_f32 v119, v119, v203, v202
	v_fma_f32 v120, v120, v203, v202
	v_fma_f32 v121, v121, v203, v202
	v_fma_f32 v122, v122, v203, v202
	v_fma_f32 v123, v123, v203, v202
	v_fma_f32 v124, v124, v203, v202
	v_fma_f32 v125, v125, v203, v202
	v_fma_f32 v126, v126, v203, v202
	v_fma_f32 v127, v127, v203, v202
	v_fma_f32 v128, v128, v203, v202
	v_fma_f32 v129, v129, v203, v202
	v_exp_f32_e32 v114, v114
	v_exp_f32_e32 v115, v115
	v_exp_f32_e32 v116, v116
	v_exp_f32_e32 v117, v117
	v_exp_f32_e32 v118, v118
	v_exp_f32_e32 v119, v119
	v_exp_f32_e32 v120, v120
	v_exp_f32_e32 v121, v121
	v_exp_f32_e32 v122, v122
	v_exp_f32_e32 v123, v123
	v_exp_f32_e32 v124, v124
	v_exp_f32_e32 v125, v125
	v_exp_f32_e32 v126, v126
	v_exp_f32_e32 v127, v127
	v_exp_f32_e32 v128, v128
	v_exp_f32_e32 v129, v129
	s_nop 0
	v_fma_f32 v177, v177, v178, v114
	v_add_f32_e32 v177, v177, v115
	v_add_f32_e32 v177, v177, v116
	v_add_f32_e32 v177, v177, v117
	v_add_f32_e32 v177, v177, v118
	v_add_f32_e32 v177, v177, v119
	v_add_f32_e32 v177, v177, v120
	v_add_f32_e32 v177, v177, v121
	v_add_f32_e32 v177, v177, v122
	v_add_f32_e32 v177, v177, v123
	v_add_f32_e32 v177, v177, v124
	v_add_f32_e32 v177, v177, v125
	v_add_f32_e32 v177, v177, v126
	v_add_f32_e32 v177, v177, v127
	v_add_f32_e32 v177, v177, v128
	v_add_f32_e32 v177, v177, v129
	v_cvt_pk_f16_f32 v130, v114, v115
	v_cvt_pk_f16_f32 v131, v116, v117
	v_cvt_pk_f16_f32 v132, v118, v119
	v_cvt_pk_f16_f32 v133, v120, v121
	v_cvt_pk_f16_f32 v134, v122, v123
	v_cvt_pk_f16_f32 v135, v124, v125
	v_cvt_pk_f16_f32 v136, v126, v127
	v_cvt_pk_f16_f32 v137, v128, v129
	v_pk_mul_f32 v[138:139], v[138:139], v[178:179] op_sel_hi:[1,0]
	v_pk_mul_f32 v[140:141], v[140:141], v[178:179] op_sel_hi:[1,0]
	v_pk_mul_f32 v[142:143], v[142:143], v[178:179] op_sel_hi:[1,0]
	v_pk_mul_f32 v[144:145], v[144:145], v[178:179] op_sel_hi:[1,0]
	v_pk_mul_f32 v[146:147], v[146:147], v[178:179] op_sel_hi:[1,0]
	v_pk_mul_f32 v[148:149], v[148:149], v[178:179] op_sel_hi:[1,0]
	v_pk_mul_f32 v[150:151], v[150:151], v[178:179] op_sel_hi:[1,0]
	v_pk_mul_f32 v[152:153], v[152:153], v[178:179] op_sel_hi:[1,0]
	s_waitcnt lgkmcnt(0)
	s_nop 1
	v_mfma_f32_16x16x32_f16 v[138:141], v[216:219], v[130:133], v[138:141]
	v_mfma_f32_16x16x32_f16 v[142:145], v[224:227], v[130:133], v[142:145]
	v_mfma_f32_16x16x32_f16 v[146:149], v[232:235], v[130:133], v[146:149]
	v_mfma_f32_16x16x32_f16 v[150:153], v[240:243], v[130:133], v[150:153]
	v_mfma_f32_16x16x32_f16 v[138:141], v[220:223], v[134:137], v[138:141]
	v_mfma_f32_16x16x32_f16 v[142:145], v[228:231], v[134:137], v[142:145]
	v_mfma_f32_16x16x32_f16 v[146:149], v[236:239], v[134:137], v[146:149]
	v_mfma_f32_16x16x32_f16 v[150:153], v[244:247], v[134:137], v[150:153]
.Lat0_kb2_end:
	s_nop 7
	s_nop 1
	v_mov_b32_e32 v201, v177
	s_nop 1
	v_permlane16_swap_b32 v201, v177
	s_nop 1
	v_add_f32_e32 v177, v177, v201
	v_mov_b32_e32 v201, v177
	s_nop 1
	v_permlane32_swap_b32 v201, v177
	s_nop 1
	v_add_f32_e32 v177, v177, v201
	v_rcp_f32_e32 v178, v177
	s_nop 0
	v_pk_mul_f32 v[138:139], v[138:139], v[178:179] op_sel_hi:[1,0]
	v_pk_mul_f32 v[140:141], v[140:141], v[178:179] op_sel_hi:[1,0]
	v_pk_mul_f32 v[142:143], v[142:143], v[178:179] op_sel_hi:[1,0]
	v_pk_mul_f32 v[144:145], v[144:145], v[178:179] op_sel_hi:[1,0]
	v_pk_mul_f32 v[146:147], v[146:147], v[178:179] op_sel_hi:[1,0]
	v_pk_mul_f32 v[148:149], v[148:149], v[178:179] op_sel_hi:[1,0]
	v_pk_mul_f32 v[150:151], v[150:151], v[178:179] op_sel_hi:[1,0]
	v_pk_mul_f32 v[152:153], v[152:153], v[178:179] op_sel_hi:[1,0]
	v_cvt_pk_f16_f32 v130, v138, v139
	v_cvt_pk_f16_f32 v131, v140, v141
	v_cvt_pk_f16_f32 v132, v142, v143
	v_cvt_pk_f16_f32 v133, v144, v145
	v_cvt_pk_f16_f32 v134, v146, v147
	v_cvt_pk_f16_f32 v135, v148, v149
	v_cvt_pk_f16_f32 v136, v150, v151
	v_cvt_pk_f16_f32 v137, v152, v153
	global_store_dwordx2 v249, v[130:131], s[48:49]
	global_store_dwordx2 v249, v[132:133], s[48:49] offset:32
	global_store_dwordx2 v249, v[134:135], s[48:49] offset:64
	global_store_dwordx2 v249, v[136:137], s[48:49] offset:96
	v_and_b32_e32 v179, 63, v182
	v_and_b32_e32 v200, 15, v179
	s_lshl_b32 s51, s58, 4
	v_add_u32_e32 v200, s51, v200
	s_lshl_b32 s51, s60, 5
	v_mul_u32_u24_e32 v200, s51, v200
	v_mov_b32_e32 v202, v176
	v_mov_b32_e32 v203, v177
	s_mov_b64 exec, 0xffff
	s_nop 1
	global_store_dwordx2 v200, v[202:203], s[16:17]
	s_nop 1
	s_mov_b64 exec, -1
; DI int otid() { int t = threadIdx.x & 255; asm volatile("" : "+v"(t)); return t; }
; template <int NKB>
; DI void attn_unit(const Params& p, int l, int mode, int grp, int head, int r0, int dil, int i0, int sub_len, int W, h16* lds) {
;     ...
;   h16* Qi = lds; h16* Ki = lds + 64 * LDH; h16* Vt = lds + 128 * LDH; h16* Pi = lds + 192 * LDH;
;   const int tid = otid(), lane = tid & 63, w = tid >> 6, r = lane & 15, q = lane >> 4;
;   const int lrow = tid >> 2, seg = tid & 3;
;   int qcol, kcol, vcol;
;   if (mode == 0) { qcol = 1024 + grp * 256 + head * 64; kcol = 1792 + grp * 256 + head * 64; vcol = 2560 + grp * 256 + head * 64; }
;   else { qcol = 4352 + head * 64; kcol = 4864 + (head >> 2) * 64; vcol = 4992 + (head >> 2) * 64; }
;   __syncthreads();
;   {
;     const size_t pos = (size_t)r0 + (size_t)dil * (i0 + lrow);
;     const h16* g = P + pos * NSM + qcol + 16 * seg;
;     img_store_nat(Qi, lrow, seg, *(const u4v*)g, *(const u4v*)(g + 8));
;   }
;   float mrow[4], lsum[4];
;   f4v O[4];
;   float m_init = -1e30f, l_init = 0.f;
;   if (mode == 1) { m_init = p.d_sink[l * 8 + head]; l_init = 1.f; }
; #pragma unroll
;   for (int i = 0; i < 4; ++i) { mrow[i] = m_init; lsum[i] = l_init; O[i] = (f4v){0.f, 0.f, 0.f, 0.f}; }
;   u4v pk0, pk1, pv0, pv1;
;     ...
;   ATT_PREFETCH(0);
;   for (int kb = 0; kb < NKB; ++kb) {
;     const int j0 = i0 - W + 64 * kb;
;     const bool inr = (j0 >= 0) && (j0 < sub_len);
;     __syncthreads();
;     img_store_nat(Ki, lrow, seg, pk0, pk1);
;     img_store_T(Vt, lrow, seg, pv0, pv1);
;     __syncthreads();
;     if (kb + 1 < NKB) ATT_PREFETCH(kb + 1);
; DI void phase_m2(const Params& p, int l, int bid, int nb, h16* lds) {
;     ...
;     if ((v -= 136) < 2048) { attn_unit<5>(p, l, 1, 0, v & 7, 0, 1, (v >> 3) * 64, SEQ, 128, lds); continue; }
.LBB0_909:
.LBB0_910:
	s_andn2_saveexec_b64 s[34:35], s[34:35]
	s_cbranch_execz .LBB0_914
	v_readfirstlane_b32 s36, v1
	v_readfirstlane_b32 s58, v182
	s_lshr_b32 s58, s58, 6
	s_sub_u32 s51, s36, 0xa8
	s_and_b32 s56, s51, 15
	s_sub_u32 s56, s56, 8
	s_and_b32 s56, s56, 15
	s_lshr_b32 s56, s56, 1
	s_lshr_b32 s57, s51, 4
	s_lshl_b32 s57, s57, 1
	s_and_b32 s59, s51, 1
	s_or_b32 s57, s57, s59
	s_lshl_b32 s56, s56, 8
	s_add_u32 s36, s56, s57
	s_and_b32 s37, s36, 7
	s_lshr_b32 s38, s36, 3
	s_lshl_b32 s38, s38, 6
	s_mov_b32 s40, 0
	s_movk_i32 s39, 0x2800
	s_mov_b32 s60, 1
	s_movk_i32 s41, 0x4000
	s_lshr_b32 s51, s37, 2
	s_lshl_b32 s51, s51, 7
	s_lshl_b32 s56, s37, 7
	s_add_u32 s53, s56, 0x2200
	s_add_u32 s54, s51, 0x2600
	s_add_u32 s55, s51, 0x2700
	v_and_b32_e32 v179, 63, v182
	v_and_b32_e32 v200, 15, v179
	v_lshrrev_b32_e32 v201, 4, v179
	v_lshlrev_b32_e32 v202, 4, v201
	v_mad_u32_u24 v2, v200, s39, v202
	v_add_u32_e32 v203, 16, v200
	v_mad_u32_u24 v3, v203, s39, v202
	v_add_u32_e32 v203, 32, v200
	v_mad_u32_u24 v4, v203, s39, v202
	v_add_u32_e32 v203, 48, v200
	v_mad_u32_u24 v5, v203, s39, v202
	s_lshl_b32 s51, s58, 4
	v_add_u32_e32 v203, s51, v200
	v_mad_u32_u24 v248, v203, s39, v202
	v_lshlrev_b32_e32 v160, 2, v201
	v_sub_u32_e32 v160, v160, v203
	v_mul_u32_u24_e32 v249, 0xa00, v203
	v_lshl_add_u32 v249, v201, 3, v249
	v_lshrrev_b32_e32 v203, 3, v179
	s_lshl_b32 s51, s58, 4
	v_add_u32_e32 v203, s51, v203
	v_and_b32_e32 v202, 7, v179
	v_lshlrev_b32_e32 v202, 4, v202
	v_mad_u32_u24 v6, v203, s39, v202
	v_add_u32_e32 v200, 8, v203
	v_mad_u32_u24 v7, v200, s39, v202
	s_movk_i32 s57, 0x90
	v_mad_u32_u24 v158, v203, s57, v183
	v_add_u32_e32 v158, v158, v202
	v_and_b32_e32 v200, 15, v179
	v_mad_u32_u24 v8, v200, s57, v183
	v_lshl_add_u32 v8, v201, 4, v8
	v_lshrrev_b32_e32 v203, 2, v179
	v_mad_u32_u24 v159, v203, s57, v183
	v_and_b32_e32 v203, 3, v179
	v_lshl_add_u32 v159, v203, 3, v159
	v_add_u32_e32 v159, 0x2400, v159
	v_xor_b32_e32 v174, 16, v179
	v_lshlrev_b32_e32 v174, 2, v174
	v_xor_b32_e32 v175, 32, v179
	v_lshlrev_b32_e32 v175, 2, v175
	s_mul_i32 s51, s60, s38
	s_add_u32 s51, s51, s40
	s_mul_i32 s56, s51, 0x2800
	s_add_u32 s56, s56, s53
	s_add_u32 s42, s0, s56
	s_addc_u32 s43, s1, 0
	global_load_dwordx4 v[10:13], v248, s[42:43]
	global_load_dwordx4 v[14:17], v248, s[42:43] offset:64
	v_readlane_b32 s48, v252, 7
	v_readlane_b32 s49, v252, 8
	s_mul_i32 s56, s38, 0xa00
	s_lshl_b32 s57, s37, 7
	s_add_u32 s56, s56, s57
	s_add_u32 s56, s56, 0x11a80600
	s_nop 2
	s_add_u32 s48, s48, s56
	s_addc_u32 s49, s49, 0
	v_readlane_b32 s18, v252, 27
	v_readlane_b32 s19, v252, 28
	s_or_b32 s56, s92, s37
	s_lshl_b32 s56, s56, 2
	s_nop 3
	s_add_u32 s18, s18, s56
	s_addc_u32 s19, s19, 0
	s_load_dword s56, s[18:19], 0x0
	v_cmp_gt_u32_e32 vcc, 16, v179
	v_cndmask_b32_e64 v177, 0, 1.0, vcc
	s_waitcnt lgkmcnt(0)
	v_mov_b32_e32 v176, s56
	v_mov_b32_e32 v138, 0
	v_mov_b32_e32 v139, 0
	v_mov_b32_e32 v140, 0
	v_mov_b32_e32 v141, 0
	v_mov_b32_e32 v142, 0
	v_mov_b32_e32 v143, 0
	v_mov_b32_e32 v144, 0
	v_mov_b32_e32 v145, 0
	v_mov_b32_e32 v146, 0
	v_mov_b32_e32 v147, 0
	v_mov_b32_e32 v148, 0
	v_mov_b32_e32 v149, 0
	v_mov_b32_e32 v150, 0
	v_mov_b32_e32 v151, 0
	v_mov_b32_e32 v152, 0
	v_mov_b32_e32 v153, 0
	s_sub_u32 s50, s38, 128
	s_cmp_ge_i32 s50, 0
	s_cselect_b32 s56, 1, 0
	s_cmp_lt_i32 s50, s41
	s_cselect_b32 s57, 1, 0
	s_and_b32 s2, s56, s57
	s_cmp_eq_u32 s2, 1
	s_cselect_b32 s50, s50, s38
	s_mul_i32 s50, s50, s60
	s_add_u32 s50, s50, s40
	s_mul_i32 s50, s50, 0x2800
	s_add_u32 s56, s50, s54
	s_add_u32 s44, s0, s56
	s_addc_u32 s45, s1, 0
	s_add_u32 s56, s50, s55
	s_add_u32 s46, s0, s56
	s_addc_u32 s47, s1, 0
	global_load_dwordx4 v[50:53], v6, s[44:45]
	global_load_dwordx4 v[54:57], v7, s[44:45]
	global_load_dwordx4 v[58:61], v6, s[46:47]
	global_load_dwordx4 v[62:65], v7, s[46:47]
	s_sub_u32 s50, s38, 64
	s_cmp_ge_i32 s50, 0
	s_cselect_b32 s56, 1, 0
	s_cmp_lt_i32 s50, s41
	s_cselect_b32 s57, 1, 0
	s_and_b32 s3, s56, s57
	s_cmp_eq_u32 s3, 1
	s_cselect_b32 s50, s50, s38
	s_mul_i32 s50, s50, s60
	s_add_u32 s50, s50, s40
	s_mul_i32 s50, s50, 0x2800
	s_add_u32 s56, s50, s54
	s_add_u32 s44, s0, s56
	s_addc_u32 s45, s1, 0
	s_add_u32 s56, s50, s55
	s_add_u32 s46, s0, s56
	s_addc_u32 s47, s1, 0
	global_load_dwordx4 v[66:69], v6, s[44:45]
	global_load_dwordx4 v[70:73], v7, s[44:45]
	global_load_dwordx4 v[74:77], v6, s[46:47]
	global_load_dwordx4 v[78:81], v7, s[46:47]
	s_waitcnt vmcnt(4)
	ds_write_b128 v158, v[50:53] offset:0
	ds_write_b128 v158, v[54:57] offset:1152
	ds_write_b128 v158, v[58:61] offset:9216
	ds_write_b128 v158, v[62:65] offset:10368
	s_waitcnt lgkmcnt(0)
	s_barrier
	s_add_u32 s50, s38, 0
	s_cmp_ge_i32 s50, 0
	s_cselect_b32 s56, 1, 0
	s_cmp_lt_i32 s50, s41
	s_cselect_b32 s57, 1, 0
	s_and_b32 s4, s56, s57
	s_cmp_eq_u32 s4, 1
	s_cselect_b32 s50, s50, s38
	s_mul_i32 s50, s50, s60
	s_add_u32 s50, s50, s40
	s_mul_i32 s50, s50, 0x2800
	s_add_u32 s56, s50, s54
	s_add_u32 s44, s0, s56
	s_addc_u32 s45, s1, 0
	s_add_u32 s56, s50, s55
	s_add_u32 s46, s0, s56
	s_addc_u32 s47, s1, 0
	global_load_dwordx4 v[50:53], v6, s[44:45]
	global_load_dwordx4 v[54:57], v7, s[44:45]
	global_load_dwordx4 v[58:61], v6, s[46:47]
	global_load_dwordx4 v[62:65], v7, s[46:47]
	s_cmp_eq_u32 s2, 1
	s_cbranch_scc0 .Lat1_kb0_end
; DI float grp16_sum(float v) { v += __shfl_xor(v, 1); v += __shfl_xor(v, 2); v += __shfl_xor(v, 4); v += __shfl_xor(v, 8); return v; }
; DI float grp16_max(float v) { v = fmaxf(v, __shfl_xor(v, 1)); v = fmaxf(v, __shfl_xor(v, 2)); v = fmaxf(v, __shfl_xor(v, 4)); v = fmaxf(v, __shfl_xor(v, 8)); return v; }
; template <int NKB>
; DI void attn_unit(const Params& p, int l, int mode, int grp, int head, int r0, int dil, int i0, int sub_len, int W, h16* lds) {
;     ...
;   for (int kb = 0; kb < NKB; ++kb) {
;     const int j0 = i0 - W + 64 * kb;
;     const bool inr = (j0 >= 0) && (j0 < sub_len);
;     __syncthreads();
;     img_store_nat(Ki, lrow, seg, pk0, pk1);
;     img_store_T(Vt, lrow, seg, pv0, pv1);
;     __syncthreads();
;     if (kb + 1 < NKB) ATT_PREFETCH(kb + 1);
;     f4v S[4];
; #pragma unroll
;     for (int i = 0; i < 4; ++i) S[i] = (f4v){0.f, 0.f, 0.f, 0.f};
;     mm64(Qi, Ki, S, w, lane);
;     float mx[4], al[4], rsum[4];
;     bool vm[4][4];
; #pragma unroll
;     for (int rg = 0; rg < 4; ++rg) {
;       const int row = 16 * w + 4 * q + rg;
;       float m_ = -1e30f;
; #pragma unroll
;       for (int nt = 0; nt < 4; ++nt) {
;         const int key = 16 * nt + r;
;         const int delta = row - key + W - 64 * kb;
;         const bool ok = inr && (delta >= -W) && (delta <= W);
;         vm[nt][rg] = ok;
;         float s = S[nt][rg] * 0.125f;
;         S[nt][rg] = s;
;         if (ok) m_ = fmaxf(m_, s);
;       }
;       mx[rg] = grp16_max(m_);
;     }
; #pragma unroll
;     for (int rg = 0; rg < 4; ++rg) {
;       const float mn = fmaxf(mrow[rg], mx[rg]);
;       al[rg] = __expf(mrow[rg] - mn);
;       mrow[rg] = mn;
;       float rs_ = 0.f;
; #pragma unroll
;       for (int nt = 0; nt < 4; ++nt) {
;         float pv = vm[nt][rg] ? __expf(S[nt][rg] - mn) : 0.f;
;         rs_ += pv;
;         Pi[(16 * w + 4 * q + rg) * LDH + 16 * nt + r] = (h16)pv;
;       }
;       rsum[rg] = grp16_sum(rs_);
;       lsum[rg] = lsum[rg] * al[rg] + rsum[rg];
;     }
; #pragma unroll
;     for (int et = 0; et < 4; ++et)
; #pragma unroll
;       for (int rg = 0; rg < 4; ++rg) O[et][rg] *= al[rg];
;     __syncthreads();
;     mm64(Pi, Vt, O, w, lane);
;   }
	ds_read_b128 v[18:21], v8 offset:0
	ds_read_b128 v[22:25], v8 offset:64
	ds_read_b128 v[26:29], v8 offset:2304
	ds_read_b128 v[30:33], v8 offset:2368
	ds_read_b128 v[34:37], v8 offset:4608
	ds_read_b128 v[38:41], v8 offset:4672
	ds_read_b128 v[42:45], v8 offset:6912
	ds_read_b128 v[46:49], v8 offset:6976
	ds_read_b64_tr_b16 v[216:217], v159
	ds_read_b64_tr_b16 v[218:219], v159 offset:2304
	ds_read_b64_tr_b16 v[220:221], v159 offset:4608
	ds_read_b64_tr_b16 v[222:223], v159 offset:6912
	ds_read_b64_tr_b16 v[224:225], v159 offset:32
	ds_read_b64_tr_b16 v[226:227], v159 offset:2336
	ds_read_b64_tr_b16 v[228:229], v159 offset:4640
	ds_read_b64_tr_b16 v[230:231], v159 offset:6944
	ds_read_b64_tr_b16 v[232:233], v159 offset:64
	ds_read_b64_tr_b16 v[234:235], v159 offset:2368
	ds_read_b64_tr_b16 v[236:237], v159 offset:4672
	ds_read_b64_tr_b16 v[238:239], v159 offset:6976
	ds_read_b64_tr_b16 v[240:241], v159 offset:96
	ds_read_b64_tr_b16 v[242:243], v159 offset:2400
	ds_read_b64_tr_b16 v[244:245], v159 offset:4704
	ds_read_b64_tr_b16 v[246:247], v159 offset:7008
	s_waitcnt lgkmcnt(15)
	v_mfma_f32_16x16x32_f16 v[114:117], v[18:21], v[10:13], 0
	v_mfma_f32_16x16x32_f16 v[118:121], v[26:29], v[10:13], 0
	v_mfma_f32_16x16x32_f16 v[122:125], v[34:37], v[10:13], 0
	v_mfma_f32_16x16x32_f16 v[126:129], v[42:45], v[10:13], 0
	v_mfma_f32_16x16x32_f16 v[114:117], v[22:25], v[14:17], v[114:117]
	v_mfma_f32_16x16x32_f16 v[118:121], v[30:33], v[14:17], v[118:121]
	v_mfma_f32_16x16x32_f16 v[122:125], v[38:41], v[14:17], v[122:125]
	v_mfma_f32_16x16x32_f16 v[126:129], v[46:49], v[14:17], v[126:129]
	s_nop 7
	s_nop 7
	v_mul_f32_e32 v114, 0x3e000000, v114
	v_mul_f32_e32 v115, 0x3e000000, v115
	v_mul_f32_e32 v116, 0x3e000000, v116
	v_mul_f32_e32 v117, 0x3e000000, v117
	v_mul_f32_e32 v118, 0x3e000000, v118
	v_mul_f32_e32 v119, 0x3e000000, v119
	v_mul_f32_e32 v120, 0x3e000000, v120
	v_mul_f32_e32 v121, 0x3e000000, v121
	v_mul_f32_e32 v122, 0x3e000000, v122
	v_mul_f32_e32 v123, 0x3e000000, v123
	v_mul_f32_e32 v124, 0x3e000000, v124
	v_mul_f32_e32 v125, 0x3e000000, v125
	v_mul_f32_e32 v126, 0x3e000000, v126
	v_mul_f32_e32 v127, 0x3e000000, v127
	v_mul_f32_e32 v128, 0x3e000000, v128
	v_mul_f32_e32 v129, 0x3e000000, v129
	v_mov_b32_e32 v200, 0xf149f2ca
	v_cmp_le_i32_e32 vcc, 0, v160
	v_cndmask_b32_e32 v114, v200, v114, vcc
	v_cmp_le_i32_e32 vcc, -1, v160
	v_cndmask_b32_e32 v115, v200, v115, vcc
	v_cmp_le_i32_e32 vcc, -2, v160
	v_cndmask_b32_e32 v116, v200, v116, vcc
	v_cmp_le_i32_e32 vcc, -3, v160
	v_cndmask_b32_e32 v117, v200, v117, vcc
	v_cmp_le_i32_e32 vcc, -16, v160
	v_cndmask_b32_e32 v118, v200, v118, vcc
	v_cmp_le_i32_e32 vcc, -17, v160
	v_cndmask_b32_e32 v119, v200, v119, vcc
	v_cmp_le_i32_e32 vcc, -18, v160
	v_cndmask_b32_e32 v120, v200, v120, vcc
	v_cmp_le_i32_e32 vcc, -19, v160
	v_cndmask_b32_e32 v121, v200, v121, vcc
	v_cmp_le_i32_e32 vcc, -32, v160
	v_cndmask_b32_e32 v122, v200, v122, vcc
	v_cmp_le_i32_e32 vcc, -33, v160
	v_cndmask_b32_e32 v123, v200, v123, vcc
	v_cmp_le_i32_e32 vcc, -34, v160
	v_cndmask_b32_e32 v124, v200, v124, vcc
	v_cmp_le_i32_e32 vcc, -35, v160
	v_cndmask_b32_e32 v125, v200, v125, vcc
	v_cmp_le_i32_e32 vcc, -48, v160
	v_cndmask_b32_e32 v126, v200, v126, vcc
	v_cmp_le_i32_e32 vcc, -49, v160
	v_cndmask_b32_e32 v127, v200, v127, vcc
	v_cmp_le_i32_e32 vcc, -50, v160
	v_cndmask_b32_e32 v128, v200, v128, vcc
	v_cmp_le_i32_e32 vcc, -51, v160
	v_cndmask_b32_e32 v129, v200, v129, vcc
	v_max3_f32 v179, v114, v115, v116
	v_max3_f32 v179, v179, v117, v118
	v_max3_f32 v179, v179, v119, v120
	v_max3_f32 v179, v179, v121, v122
	v_max3_f32 v179, v179, v123, v124
	v_max3_f32 v179, v179, v125, v126
	v_max3_f32 v179, v179, v127, v128
	v_max_f32_e32 v179, v179, v129
	v_mov_b32_e32 v201, v179
	s_nop 1
	v_permlane16_swap_b32 v201, v179
	s_nop 1
	v_max_f32_e32 v179, v179, v201
	v_mov_b32_e32 v201, v179
	s_nop 1
	v_permlane32_swap_b32 v201, v179
	s_nop 1
	v_max3_f32 v179, v179, v201, v176
	v_sub_f32_e32 v178, v176, v179
	v_mul_f32_e32 v178, 0x3fb8aa3b, v178
	v_exp_f32_e32 v178, v178
	v_mov_b32_e32 v176, v179
	v_mul_f32_e32 v202, 0xbfb8aa3b, v179
	v_mov_b32_e32 v203, 0x3fb8aa3b
	v_fma_f32 v114, v114, v203, v202
	v_fma_f32 v115, v115, v203, v202
	v_fma_f32 v116, v116, v203, v202
	v_fma_f32 v117, v117, v203, v202
	v_fma_f32 v118, v118, v203, v202
	v_fma_f32 v119, v119, v203, v202
	v_fma_f32 v120, v120, v203, v202
	v_fma_f32 v121, v121, v203, v202
	v_fma_f32 v122, v122, v203, v202
	v_fma_f32 v123, v123, v203, v202
	v_fma_f32 v124, v124, v203, v202
	v_fma_f32 v125, v125, v203, v202
	v_fma_f32 v126, v126, v203, v202
	v_fma_f32 v127, v127, v203, v202
	v_fma_f32 v128, v128, v203, v202
	v_fma_f32 v129, v129, v203, v202
	v_exp_f32_e32 v114, v114
	v_exp_f32_e32 v115, v115
	v_exp_f32_e32 v116, v116
	v_exp_f32_e32 v117, v117
	v_exp_f32_e32 v118, v118
	v_exp_f32_e32 v119, v119
	v_exp_f32_e32 v120, v120
	v_exp_f32_e32 v121, v121
	v_exp_f32_e32 v122, v122
	v_exp_f32_e32 v123, v123
	v_exp_f32_e32 v124, v124
	v_exp_f32_e32 v125, v125
	v_exp_f32_e32 v126, v126
	v_exp_f32_e32 v127, v127
	v_exp_f32_e32 v128, v128
	v_exp_f32_e32 v129, v129
	s_nop 0
	v_fma_f32 v177, v177, v178, v114
	v_add_f32_e32 v177, v177, v115
	v_add_f32_e32 v177, v177, v116
	v_add_f32_e32 v177, v177, v117
	v_add_f32_e32 v177, v177, v118
	v_add_f32_e32 v177, v177, v119
	v_add_f32_e32 v177, v177, v120
	v_add_f32_e32 v177, v177, v121
	v_add_f32_e32 v177, v177, v122
	v_add_f32_e32 v177, v177, v123
	v_add_f32_e32 v177, v177, v124
	v_add_f32_e32 v177, v177, v125
	v_add_f32_e32 v177, v177, v126
	v_add_f32_e32 v177, v177, v127
	v_add_f32_e32 v177, v177, v128
	v_add_f32_e32 v177, v177, v129
	v_cvt_pk_f16_f32 v130, v114, v115
	v_cvt_pk_f16_f32 v131, v116, v117
	v_cvt_pk_f16_f32 v132, v118, v119
	v_cvt_pk_f16_f32 v133, v120, v121
	v_cvt_pk_f16_f32 v134, v122, v123
	v_cvt_pk_f16_f32 v135, v124, v125
	v_cvt_pk_f16_f32 v136, v126, v127
	v_cvt_pk_f16_f32 v137, v128, v129
	v_pk_mul_f32 v[138:139], v[138:139], v[178:179] op_sel_hi:[1,0]
	v_pk_mul_f32 v[140:141], v[140:141], v[178:179] op_sel_hi:[1,0]
	v_pk_mul_f32 v[142:143], v[142:143], v[178:179] op_sel_hi:[1,0]
	v_pk_mul_f32 v[144:145], v[144:145], v[178:179] op_sel_hi:[1,0]
	v_pk_mul_f32 v[146:147], v[146:147], v[178:179] op_sel_hi:[1,0]
	v_pk_mul_f32 v[148:149], v[148:149], v[178:179] op_sel_hi:[1,0]
	v_pk_mul_f32 v[150:151], v[150:151], v[178:179] op_sel_hi:[1,0]
	v_pk_mul_f32 v[152:153], v[152:153], v[178:179] op_sel_hi:[1,0]
	s_waitcnt lgkmcnt(0)
	s_nop 1
	v_mfma_f32_16x16x32_f16 v[138:141], v[216:219], v[130:133], v[138:141]
	v_mfma_f32_16x16x32_f16 v[142:145], v[224:227], v[130:133], v[142:145]
	v_mfma_f32_16x16x32_f16 v[146:149], v[232:235], v[130:133], v[146:149]
	v_mfma_f32_16x16x32_f16 v[150:153], v[240:243], v[130:133], v[150:153]
	v_mfma_f32_16x16x32_f16 v[138:141], v[220:223], v[134:137], v[138:141]
	v_mfma_f32_16x16x32_f16 v[142:145], v[228:231], v[134:137], v[142:145]
	v_mfma_f32_16x16x32_f16 v[146:149], v[236:239], v[134:137], v[146:149]
	v_mfma_f32_16x16x32_f16 v[150:153], v[244:247], v[134:137], v[150:153]
; DI float grp16_sum(float v) { v += __shfl_xor(v, 1); v += __shfl_xor(v, 2); v += __shfl_xor(v, 4); v += __shfl_xor(v, 8); return v; }
; DI float grp16_max(float v) { v = fmaxf(v, __shfl_xor(v, 1)); v = fmaxf(v, __shfl_xor(v, 2)); v = fmaxf(v, __shfl_xor(v, 4)); v = fmaxf(v, __shfl_xor(v, 8)); return v; }
; template <int NKB>
; DI void attn_unit(const Params& p, int l, int mode, int grp, int head, int r0, int dil, int i0, int sub_len, int W, h16* lds) {
;     ...
;   ATT_PREFETCH(0);
;   for (int kb = 0; kb < NKB; ++kb) {
;     const int j0 = i0 - W + 64 * kb;
;     const bool inr = (j0 >= 0) && (j0 < sub_len);
;     __syncthreads();
;     img_store_nat(Ki, lrow, seg, pk0, pk1);
;     img_store_T(Vt, lrow, seg, pv0, pv1);
;     __syncthreads();
;     if (kb + 1 < NKB) ATT_PREFETCH(kb + 1);
;     f4v S[4];
; #pragma unroll
;     for (int i = 0; i < 4; ++i) S[i] = (f4v){0.f, 0.f, 0.f, 0.f};
;     mm64(Qi, Ki, S, w, lane);
;     float mx[4], al[4], rsum[4];
;     bool vm[4][4];
; #pragma unroll
;     for (int rg = 0; rg < 4; ++rg) {
;       const int row = 16 * w + 4 * q + rg;
;       float m_ = -1e30f;
; #pragma unroll
;       for (int nt = 0; nt < 4; ++nt) {
;         const int key = 16 * nt + r;
;         const int delta = row - key + W - 64 * kb;
;         const bool ok = inr && (delta >= -W) && (delta <= W);
;         vm[nt][rg] = ok;
;         float s = S[nt][rg] * 0.125f;
;         S[nt][rg] = s;
;         if (ok) m_ = fmaxf(m_, s);
;       }
;       mx[rg] = grp16_max(m_);
;     }
; #pragma unroll
;     for (int rg = 0; rg < 4; ++rg) {
;       const float mn = fmaxf(mrow[rg], mx[rg]);
;       al[rg] = __expf(mrow[rg] - mn);
;       mrow[rg] = mn;
;       float rs_ = 0.f;
; #pragma unroll
;       for (int nt = 0; nt < 4; ++nt) {
;         float pv = vm[nt][rg] ? __expf(S[nt][rg] - mn) : 0.f;
;         rs_ += pv;
;         Pi[(16 * w + 4 * q + rg) * LDH + 16 * nt + r] = (h16)pv;
;       }
;       rsum[rg] = grp16_sum(rs_);
;       lsum[rg] = lsum[rg] * al[rg] + rsum[rg];
;     }
; #pragma unroll
;     for (int et = 0; et < 4; ++et)
; #pragma unroll
;       for (int rg = 0; rg < 4; ++rg) O[et][rg] *= al[rg];
;     __syncthreads();
;     mm64(Pi, Vt, O, w, lane);
;   }
.Lat1_kb0_end:
	s_waitcnt vmcnt(4)
	ds_write_b128 v158, v[66:69] offset:18432
	ds_write_b128 v158, v[70:73] offset:19584
	ds_write_b128 v158, v[74:77] offset:27648
	ds_write_b128 v158, v[78:81] offset:28800
	s_waitcnt lgkmcnt(0)
	s_barrier
	s_add_u32 s50, s38, 64
	s_cmp_ge_i32 s50, 0
	s_cselect_b32 s56, 1, 0
	s_cmp_lt_i32 s50, s41
	s_cselect_b32 s57, 1, 0
	s_and_b32 s5, s56, s57
	s_cmp_eq_u32 s5, 1
	s_cselect_b32 s50, s50, s38
	s_mul_i32 s50, s50, s60
	s_add_u32 s50, s50, s40
	s_mul_i32 s50, s50, 0x2800
	s_add_u32 s56, s50, s54
	s_add_u32 s44, s0, s56
	s_addc_u32 s45, s1, 0
	s_add_u32 s56, s50, s55
	s_add_u32 s46, s0, s56
	s_addc_u32 s47, s1, 0
	global_load_dwordx4 v[66:69], v6, s[44:45]
	global_load_dwordx4 v[70:73], v7, s[44:45]
	global_load_dwordx4 v[74:77], v6, s[46:47]
	global_load_dwordx4 v[78:81], v7, s[46:47]
	s_cmp_eq_u32 s3, 1
	s_cbranch_scc0 .Lat1_kb1_end
	ds_read_b128 v[18:21], v8 offset:18432
	ds_read_b128 v[22:25], v8 offset:18496
	ds_read_b128 v[26:29], v8 offset:20736
	ds_read_b128 v[30:33], v8 offset:20800
	ds_read_b128 v[34:37], v8 offset:23040
	ds_read_b128 v[38:41], v8 offset:23104
	ds_read_b128 v[42:45], v8 offset:25344
	ds_read_b128 v[46:49], v8 offset:25408
	ds_read_b64_tr_b16 v[216:217], v159 offset:18432
	ds_read_b64_tr_b16 v[218:219], v159 offset:20736
	ds_read_b64_tr_b16 v[220:221], v159 offset:23040
	ds_read_b64_tr_b16 v[222:223], v159 offset:25344
	ds_read_b64_tr_b16 v[224:225], v159 offset:18464
	ds_read_b64_tr_b16 v[226:227], v159 offset:20768
	ds_read_b64_tr_b16 v[228:229], v159 offset:23072
	ds_read_b64_tr_b16 v[230:231], v159 offset:25376
	ds_read_b64_tr_b16 v[232:233], v159 offset:18496
	ds_read_b64_tr_b16 v[234:235], v159 offset:20800
	ds_read_b64_tr_b16 v[236:237], v159 offset:23104
	ds_read_b64_tr_b16 v[238:239], v159 offset:25408
	ds_read_b64_tr_b16 v[240:241], v159 offset:18528
	ds_read_b64_tr_b16 v[242:243], v159 offset:20832
	ds_read_b64_tr_b16 v[244:245], v159 offset:23136
	ds_read_b64_tr_b16 v[246:247], v159 offset:25440
	s_waitcnt lgkmcnt(15)
	v_mfma_f32_16x16x32_f16 v[114:117], v[18:21], v[10:13], 0
	v_mfma_f32_16x16x32_f16 v[118:121], v[26:29], v[10:13], 0
	v_mfma_f32_16x16x32_f16 v[122:125], v[34:37], v[10:13], 0
	v_mfma_f32_16x16x32_f16 v[126:129], v[42:45], v[10:13], 0
	v_mfma_f32_16x16x32_f16 v[114:117], v[22:25], v[14:17], v[114:117]
	v_mfma_f32_16x16x32_f16 v[118:121], v[30:33], v[14:17], v[118:121]
	v_mfma_f32_16x16x32_f16 v[122:125], v[38:41], v[14:17], v[122:125]
	v_mfma_f32_16x16x32_f16 v[126:129], v[46:49], v[14:17], v[126:129]
	s_nop 7
	s_nop 7
	v_mul_f32_e32 v114, 0x3e000000, v114
	v_mul_f32_e32 v115, 0x3e000000, v115
	v_mul_f32_e32 v116, 0x3e000000, v116
	v_mul_f32_e32 v117, 0x3e000000, v117
	v_mul_f32_e32 v118, 0x3e000000, v118
	v_mul_f32_e32 v119, 0x3e000000, v119
	v_mul_f32_e32 v120, 0x3e000000, v120
	v_mul_f32_e32 v121, 0x3e000000, v121
	v_mul_f32_e32 v122, 0x3e000000, v122
	v_mul_f32_e32 v123, 0x3e000000, v123
	v_mul_f32_e32 v124, 0x3e000000, v124
	v_mul_f32_e32 v125, 0x3e000000, v125
	v_mul_f32_e32 v126, 0x3e000000, v126
	v_mul_f32_e32 v127, 0x3e000000, v127
	v_mul_f32_e32 v128, 0x3e000000, v128
	v_mul_f32_e32 v129, 0x3e000000, v129
	v_max3_f32 v179, v114, v115, v116
	v_max3_f32 v179, v179, v117, v118
	v_max3_f32 v179, v179, v119, v120
	v_max3_f32 v179, v179, v121, v122
	v_max3_f32 v179, v179, v123, v124
	v_max3_f32 v179, v179, v125, v126
	v_max3_f32 v179, v179, v127, v128
	v_max_f32_e32 v179, v179, v129
	v_mov_b32_e32 v201, v179
	s_nop 1
	v_permlane16_swap_b32 v201, v179
	s_nop 1
	v_max_f32_e32 v179, v179, v201
	v_mov_b32_e32 v201, v179
	s_nop 1
	v_permlane32_swap_b32 v201, v179
	s_nop 1
	v_max3_f32 v179, v179, v201, v176
	v_sub_f32_e32 v178, v176, v179
	v_mul_f32_e32 v178, 0x3fb8aa3b, v178
	v_exp_f32_e32 v178, v178
	v_mov_b32_e32 v176, v179
	v_mul_f32_e32 v202, 0xbfb8aa3b, v179
	v_mov_b32_e32 v203, 0x3fb8aa3b
	v_fma_f32 v114, v114, v203, v202
	v_fma_f32 v115, v115, v203, v202
	v_fma_f32 v116, v116, v203, v202
	v_fma_f32 v117, v117, v203, v202
	v_fma_f32 v118, v118, v203, v202
	v_fma_f32 v119, v119, v203, v202
	v_fma_f32 v120, v120, v203, v202
	v_fma_f32 v121, v121, v203, v202
	v_fma_f32 v122, v122, v203, v202
	v_fma_f32 v123, v123, v203, v202
	v_fma_f32 v124, v124, v203, v202
	v_fma_f32 v125, v125, v203, v202
	v_fma_f32 v126, v126, v203, v202
	v_fma_f32 v127, v127, v203, v202
	v_fma_f32 v128, v128, v203, v202
	v_fma_f32 v129, v129, v203, v202
	v_exp_f32_e32 v114, v114
	v_exp_f32_e32 v115, v115
	v_exp_f32_e32 v116, v116
	v_exp_f32_e32 v117, v117
	v_exp_f32_e32 v118, v118
	v_exp_f32_e32 v119, v119
	v_exp_f32_e32 v120, v120
	v_exp_f32_e32 v121, v121
	v_exp_f32_e32 v122, v122
	v_exp_f32_e32 v123, v123
	v_exp_f32_e32 v124, v124
	v_exp_f32_e32 v125, v125
	v_exp_f32_e32 v126, v126
	v_exp_f32_e32 v127, v127
	v_exp_f32_e32 v128, v128
	v_exp_f32_e32 v129, v129
	s_nop 0
	v_fma_f32 v177, v177, v178, v114
	v_add_f32_e32 v177, v177, v115
	v_add_f32_e32 v177, v177, v116
	v_add_f32_e32 v177, v177, v117
	v_add_f32_e32 v177, v177, v118
	v_add_f32_e32 v177, v177, v119
	v_add_f32_e32 v177, v177, v120
	v_add_f32_e32 v177, v177, v121
	v_add_f32_e32 v177, v177, v122
	v_add_f32_e32 v177, v177, v123
	v_add_f32_e32 v177, v177, v124
	v_add_f32_e32 v177, v177, v125
	v_add_f32_e32 v177, v177, v126
	v_add_f32_e32 v177, v177, v127
	v_add_f32_e32 v177, v177, v128
	v_add_f32_e32 v177, v177, v129
	v_cvt_pk_f16_f32 v130, v114, v115
	v_cvt_pk_f16_f32 v131, v116, v117
	v_cvt_pk_f16_f32 v132, v118, v119
	v_cvt_pk_f16_f32 v133, v120, v121
	v_cvt_pk_f16_f32 v134, v122, v123
	v_cvt_pk_f16_f32 v135, v124, v125
	v_cvt_pk_f16_f32 v136, v126, v127
	v_cvt_pk_f16_f32 v137, v128, v129
	v_pk_mul_f32 v[138:139], v[138:139], v[178:179] op_sel_hi:[1,0]
	v_pk_mul_f32 v[140:141], v[140:141], v[178:179] op_sel_hi:[1,0]
	v_pk_mul_f32 v[142:143], v[142:143], v[178:179] op_sel_hi:[1,0]
	v_pk_mul_f32 v[144:145], v[144:145], v[178:179] op_sel_hi:[1,0]
	v_pk_mul_f32 v[146:147], v[146:147], v[178:179] op_sel_hi:[1,0]
	v_pk_mul_f32 v[148:149], v[148:149], v[178:179] op_sel_hi:[1,0]
	v_pk_mul_f32 v[150:151], v[150:151], v[178:179] op_sel_hi:[1,0]
	v_pk_mul_f32 v[152:153], v[152:153], v[178:179] op_sel_hi:[1,0]
	s_waitcnt lgkmcnt(0)
	s_nop 1
	v_mfma_f32_16x16x32_f16 v[138:141], v[216:219], v[130:133], v[138:141]
	v_mfma_f32_16x16x32_f16 v[142:145], v[224:227], v[130:133], v[142:145]
	v_mfma_f32_16x16x32_f16 v[146:149], v[232:235], v[130:133], v[146:149]
	v_mfma_f32_16x16x32_f16 v[150:153], v[240:243], v[130:133], v[150:153]
	v_mfma_f32_16x16x32_f16 v[138:141], v[220:223], v[134:137], v[138:141]
	v_mfma_f32_16x16x32_f16 v[142:145], v[228:231], v[134:137], v[142:145]
	v_mfma_f32_16x16x32_f16 v[146:149], v[236:239], v[134:137], v[146:149]
	v_mfma_f32_16x16x32_f16 v[150:153], v[244:247], v[134:137], v[150:153]
; DI float grp16_sum(float v) { v += __shfl_xor(v, 1); v += __shfl_xor(v, 2); v += __shfl_xor(v, 4); v += __shfl_xor(v, 8); return v; }
; DI float grp16_max(float v) { v = fmaxf(v, __shfl_xor(v, 1)); v = fmaxf(v, __shfl_xor(v, 2)); v = fmaxf(v, __shfl_xor(v, 4)); v = fmaxf(v, __shfl_xor(v, 8)); return v; }
; template <int NKB>
; DI void attn_unit(const Params& p, int l, int mode, int grp, int head, int r0, int dil, int i0, int sub_len, int W, h16* lds) {
;     ...
;   ATT_PREFETCH(0);
;   for (int kb = 0; kb < NKB; ++kb) {
;     const int j0 = i0 - W + 64 * kb;
;     const bool inr = (j0 >= 0) && (j0 < sub_len);
;     __syncthreads();
;     img_store_nat(Ki, lrow, seg, pk0, pk1);
;     img_store_T(Vt, lrow, seg, pv0, pv1);
;     __syncthreads();
;     if (kb + 1 < NKB) ATT_PREFETCH(kb + 1);
;     f4v S[4];
; #pragma unroll
;     for (int i = 0; i < 4; ++i) S[i] = (f4v){0.f, 0.f, 0.f, 0.f};
;     mm64(Qi, Ki, S, w, lane);
;     float mx[4], al[4], rsum[4];
;     bool vm[4][4];
; #pragma unroll
;     for (int rg = 0; rg < 4; ++rg) {
;       const int row = 16 * w + 4 * q + rg;
;       float m_ = -1e30f;
; #pragma unroll
;       for (int nt = 0; nt < 4; ++nt) {
;         const int key = 16 * nt + r;
;         const int delta = row - key + W - 64 * kb;
;         const bool ok = inr && (delta >= -W) && (delta <= W);
;         vm[nt][rg] = ok;
;         float s = S[nt][rg] * 0.125f;
;         S[nt][rg] = s;
;         if (ok) m_ = fmaxf(m_, s);
;       }
;       mx[rg] = grp16_max(m_);
;     }
; #pragma unroll
;     for (int rg = 0; rg < 4; ++rg) {
;       const float mn = fmaxf(mrow[rg], mx[rg]);
;       al[rg] = __expf(mrow[rg] - mn);
;       mrow[rg] = mn;
;       float rs_ = 0.f;
; #pragma unroll
;       for (int nt = 0; nt < 4; ++nt) {
;         float pv = vm[nt][rg] ? __expf(S[nt][rg] - mn) : 0.f;
;         rs_ += pv;
;         Pi[(16 * w + 4 * q + rg) * LDH + 16 * nt + r] = (h16)pv;
;       }
;       rsum[rg] = grp16_sum(rs_);
;       lsum[rg] = lsum[rg] * al[rg] + rsum[rg];
;     }
; #pragma unroll
;     for (int et = 0; et < 4; ++et)
; #pragma unroll
;       for (int rg = 0; rg < 4; ++rg) O[et][rg] *= al[rg];
;     __syncthreads();
;     mm64(Pi, Vt, O, w, lane);
;   }
.Lat1_kb1_end:
	s_waitcnt vmcnt(4)
	ds_write_b128 v158, v[50:53] offset:36864
	ds_write_b128 v158, v[54:57] offset:38016
	ds_write_b128 v158, v[58:61] offset:46080
	ds_write_b128 v158, v[62:65] offset:47232
	s_waitcnt lgkmcnt(0)
	s_barrier
	s_add_u32 s50, s38, 128
	s_cmp_ge_i32 s50, 0
	s_cselect_b32 s56, 1, 0
	s_cmp_lt_i32 s50, s41
	s_cselect_b32 s57, 1, 0
	s_and_b32 s6, s56, s57
	s_cmp_eq_u32 s6, 1
	s_cselect_b32 s50, s50, s38
	s_mul_i32 s50, s50, s60
	s_add_u32 s50, s50, s40
	s_mul_i32 s50, s50, 0x2800
	s_add_u32 s56, s50, s54
	s_add_u32 s44, s0, s56
	s_addc_u32 s45, s1, 0
	s_add_u32 s56, s50, s55
	s_add_u32 s46, s0, s56
	s_addc_u32 s47, s1, 0
	global_load_dwordx4 v[50:53], v6, s[44:45]
	global_load_dwordx4 v[54:57], v7, s[44:45]
	global_load_dwordx4 v[58:61], v6, s[46:47]
	global_load_dwordx4 v[62:65], v7, s[46:47]
	s_cmp_eq_u32 s4, 1
	s_cbranch_scc0 .Lat1_kb2_end
	ds_read_b128 v[18:21], v8 offset:36864
	ds_read_b128 v[22:25], v8 offset:36928
	ds_read_b128 v[26:29], v8 offset:39168
	ds_read_b128 v[30:33], v8 offset:39232
	ds_read_b128 v[34:37], v8 offset:41472
	ds_read_b128 v[38:41], v8 offset:41536
	ds_read_b128 v[42:45], v8 offset:43776
	ds_read_b128 v[46:49], v8 offset:43840
	ds_read_b64_tr_b16 v[216:217], v159 offset:36864
	ds_read_b64_tr_b16 v[218:219], v159 offset:39168
	ds_read_b64_tr_b16 v[220:221], v159 offset:41472
	ds_read_b64_tr_b16 v[222:223], v159 offset:43776
	ds_read_b64_tr_b16 v[224:225], v159 offset:36896
	ds_read_b64_tr_b16 v[226:227], v159 offset:39200
	ds_read_b64_tr_b16 v[228:229], v159 offset:41504
	ds_read_b64_tr_b16 v[230:231], v159 offset:43808
	ds_read_b64_tr_b16 v[232:233], v159 offset:36928
	ds_read_b64_tr_b16 v[234:235], v159 offset:39232
	ds_read_b64_tr_b16 v[236:237], v159 offset:41536
	ds_read_b64_tr_b16 v[238:239], v159 offset:43840
	ds_read_b64_tr_b16 v[240:241], v159 offset:36960
	ds_read_b64_tr_b16 v[242:243], v159 offset:39264
	ds_read_b64_tr_b16 v[244:245], v159 offset:41568
	ds_read_b64_tr_b16 v[246:247], v159 offset:43872
	s_waitcnt lgkmcnt(15)
	v_mfma_f32_16x16x32_f16 v[114:117], v[18:21], v[10:13], 0
	v_mfma_f32_16x16x32_f16 v[118:121], v[26:29], v[10:13], 0
	v_mfma_f32_16x16x32_f16 v[122:125], v[34:37], v[10:13], 0
	v_mfma_f32_16x16x32_f16 v[126:129], v[42:45], v[10:13], 0
	v_mfma_f32_16x16x32_f16 v[114:117], v[22:25], v[14:17], v[114:117]
	v_mfma_f32_16x16x32_f16 v[118:121], v[30:33], v[14:17], v[118:121]
	v_mfma_f32_16x16x32_f16 v[122:125], v[38:41], v[14:17], v[122:125]
	v_mfma_f32_16x16x32_f16 v[126:129], v[46:49], v[14:17], v[126:129]
	s_nop 7
	s_nop 7
	v_mul_f32_e32 v114, 0x3e000000, v114
	v_mul_f32_e32 v115, 0x3e000000, v115
	v_mul_f32_e32 v116, 0x3e000000, v116
	v_mul_f32_e32 v117, 0x3e000000, v117
	v_mul_f32_e32 v118, 0x3e000000, v118
	v_mul_f32_e32 v119, 0x3e000000, v119
	v_mul_f32_e32 v120, 0x3e000000, v120
	v_mul_f32_e32 v121, 0x3e000000, v121
	v_mul_f32_e32 v122, 0x3e000000, v122
	v_mul_f32_e32 v123, 0x3e000000, v123
	v_mul_f32_e32 v124, 0x3e000000, v124
	v_mul_f32_e32 v125, 0x3e000000, v125
	v_mul_f32_e32 v126, 0x3e000000, v126
	v_mul_f32_e32 v127, 0x3e000000, v127
	v_mul_f32_e32 v128, 0x3e000000, v128
	v_mul_f32_e32 v129, 0x3e000000, v129
	v_max3_f32 v179, v114, v115, v116
	v_max3_f32 v179, v179, v117, v118
	v_max3_f32 v179, v179, v119, v120
	v_max3_f32 v179, v179, v121, v122
	v_max3_f32 v179, v179, v123, v124
	v_max3_f32 v179, v179, v125, v126
	v_max3_f32 v179, v179, v127, v128
	v_max_f32_e32 v179, v179, v129
	v_mov_b32_e32 v201, v179
	s_nop 1
	v_permlane16_swap_b32 v201, v179
	s_nop 1
	v_max_f32_e32 v179, v179, v201
	v_mov_b32_e32 v201, v179
	s_nop 1
	v_permlane32_swap_b32 v201, v179
	s_nop 1
	v_max3_f32 v179, v179, v201, v176
	v_sub_f32_e32 v178, v176, v179
	v_mul_f32_e32 v178, 0x3fb8aa3b, v178
	v_exp_f32_e32 v178, v178
	v_mov_b32_e32 v176, v179
	v_mul_f32_e32 v202, 0xbfb8aa3b, v179
	v_mov_b32_e32 v203, 0x3fb8aa3b
	v_fma_f32 v114, v114, v203, v202
	v_fma_f32 v115, v115, v203, v202
	v_fma_f32 v116, v116, v203, v202
	v_fma_f32 v117, v117, v203, v202
	v_fma_f32 v118, v118, v203, v202
	v_fma_f32 v119, v119, v203, v202
	v_fma_f32 v120, v120, v203, v202
	v_fma_f32 v121, v121, v203, v202
	v_fma_f32 v122, v122, v203, v202
	v_fma_f32 v123, v123, v203, v202
	v_fma_f32 v124, v124, v203, v202
	v_fma_f32 v125, v125, v203, v202
	v_fma_f32 v126, v126, v203, v202
	v_fma_f32 v127, v127, v203, v202
	v_fma_f32 v128, v128, v203, v202
	v_fma_f32 v129, v129, v203, v202
	v_exp_f32_e32 v114, v114
	v_exp_f32_e32 v115, v115
	v_exp_f32_e32 v116, v116
	v_exp_f32_e32 v117, v117
	v_exp_f32_e32 v118, v118
	v_exp_f32_e32 v119, v119
	v_exp_f32_e32 v120, v120
	v_exp_f32_e32 v121, v121
	v_exp_f32_e32 v122, v122
	v_exp_f32_e32 v123, v123
	v_exp_f32_e32 v124, v124
	v_exp_f32_e32 v125, v125
	v_exp_f32_e32 v126, v126
	v_exp_f32_e32 v127, v127
	v_exp_f32_e32 v128, v128
	v_exp_f32_e32 v129, v129
	s_nop 0
	v_fma_f32 v177, v177, v178, v114
	v_add_f32_e32 v177, v177, v115
	v_add_f32_e32 v177, v177, v116
	v_add_f32_e32 v177, v177, v117
	v_add_f32_e32 v177, v177, v118
	v_add_f32_e32 v177, v177, v119
	v_add_f32_e32 v177, v177, v120
	v_add_f32_e32 v177, v177, v121
	v_add_f32_e32 v177, v177, v122
	v_add_f32_e32 v177, v177, v123
	v_add_f32_e32 v177, v177, v124
	v_add_f32_e32 v177, v177, v125
	v_add_f32_e32 v177, v177, v126
	v_add_f32_e32 v177, v177, v127
	v_add_f32_e32 v177, v177, v128
	v_add_f32_e32 v177, v177, v129
	v_cvt_pk_f16_f32 v130, v114, v115
	v_cvt_pk_f16_f32 v131, v116, v117
	v_cvt_pk_f16_f32 v132, v118, v119
	v_cvt_pk_f16_f32 v133, v120, v121
	v_cvt_pk_f16_f32 v134, v122, v123
	v_cvt_pk_f16_f32 v135, v124, v125
	v_cvt_pk_f16_f32 v136, v126, v127
	v_cvt_pk_f16_f32 v137, v128, v129
	v_pk_mul_f32 v[138:139], v[138:139], v[178:179] op_sel_hi:[1,0]
	v_pk_mul_f32 v[140:141], v[140:141], v[178:179] op_sel_hi:[1,0]
	v_pk_mul_f32 v[142:143], v[142:143], v[178:179] op_sel_hi:[1,0]
	v_pk_mul_f32 v[144:145], v[144:145], v[178:179] op_sel_hi:[1,0]
	v_pk_mul_f32 v[146:147], v[146:147], v[178:179] op_sel_hi:[1,0]
	v_pk_mul_f32 v[148:149], v[148:149], v[178:179] op_sel_hi:[1,0]
	v_pk_mul_f32 v[150:151], v[150:151], v[178:179] op_sel_hi:[1,0]
	v_pk_mul_f32 v[152:153], v[152:153], v[178:179] op_sel_hi:[1,0]
	s_waitcnt lgkmcnt(0)
	s_nop 1
	v_mfma_f32_16x16x32_f16 v[138:141], v[216:219], v[130:133], v[138:141]
	v_mfma_f32_16x16x32_f16 v[142:145], v[224:227], v[130:133], v[142:145]
	v_mfma_f32_16x16x32_f16 v[146:149], v[232:235], v[130:133], v[146:149]
	v_mfma_f32_16x16x32_f16 v[150:153], v[240:243], v[130:133], v[150:153]
	v_mfma_f32_16x16x32_f16 v[138:141], v[220:223], v[134:137], v[138:141]
	v_mfma_f32_16x16x32_f16 v[142:145], v[228:231], v[134:137], v[142:145]
	v_mfma_f32_16x16x32_f16 v[146:149], v[236:239], v[134:137], v[146:149]
	v_mfma_f32_16x16x32_f16 v[150:153], v[244:247], v[134:137], v[150:153]
; DI float grp16_sum(float v) { v += __shfl_xor(v, 1); v += __shfl_xor(v, 2); v += __shfl_xor(v, 4); v += __shfl_xor(v, 8); return v; }
; DI float grp16_max(float v) { v = fmaxf(v, __shfl_xor(v, 1)); v = fmaxf(v, __shfl_xor(v, 2)); v = fmaxf(v, __shfl_xor(v, 4)); v = fmaxf(v, __shfl_xor(v, 8)); return v; }
; template <int NKB>
; DI void attn_unit(const Params& p, int l, int mode, int grp, int head, int r0, int dil, int i0, int sub_len, int W, h16* lds) {
;     ...
;   for (int kb = 0; kb < NKB; ++kb) {
;     const int j0 = i0 - W + 64 * kb;
;     const bool inr = (j0 >= 0) && (j0 < sub_len);
;     __syncthreads();
;     img_store_nat(Ki, lrow, seg, pk0, pk1);
;     img_store_T(Vt, lrow, seg, pv0, pv1);
;     __syncthreads();
;     if (kb + 1 < NKB) ATT_PREFETCH(kb + 1);
;     f4v S[4];
; #pragma unroll
;     for (int i = 0; i < 4; ++i) S[i] = (f4v){0.f, 0.f, 0.f, 0.f};
;     mm64(Qi, Ki, S, w, lane);
;     float mx[4], al[4], rsum[4];
;     bool vm[4][4];
; #pragma unroll
;     for (int rg = 0; rg < 4; ++rg) {
;       const int row = 16 * w + 4 * q + rg;
;       float m_ = -1e30f;
; #pragma unroll
;       for (int nt = 0; nt < 4; ++nt) {
;         const int key = 16 * nt + r;
;         const int delta = row - key + W - 64 * kb;
;         const bool ok = inr && (delta >= -W) && (delta <= W);
;         vm[nt][rg] = ok;
;         float s = S[nt][rg] * 0.125f;
;         S[nt][rg] = s;
;         if (ok) m_ = fmaxf(m_, s);
;       }
;       mx[rg] = grp16_max(m_);
;     }
; #pragma unroll
;     for (int rg = 0; rg < 4; ++rg) {
;       const float mn = fmaxf(mrow[rg], mx[rg]);
;       al[rg] = __expf(mrow[rg] - mn);
;       mrow[rg] = mn;
;       float rs_ = 0.f;
; #pragma unroll
;       for (int nt = 0; nt < 4; ++nt) {
;         float pv = vm[nt][rg] ? __expf(S[nt][rg] - mn) : 0.f;
;         rs_ += pv;
;         Pi[(16 * w + 4 * q + rg) * LDH + 16 * nt + r] = (h16)pv;
;       }
;       rsum[rg] = grp16_sum(rs_);
;       lsum[rg] = lsum[rg] * al[rg] + rsum[rg];
;     }
; #pragma unroll
;     for (int et = 0; et < 4; ++et)
; #pragma unroll
;       for (int rg = 0; rg < 4; ++rg) O[et][rg] *= al[rg];
;     __syncthreads();
;     mm64(Pi, Vt, O, w, lane);
;   }
.Lat1_kb2_end:
	s_waitcnt vmcnt(4)
	ds_write_b128 v158, v[66:69] offset:0
	ds_write_b128 v158, v[70:73] offset:1152
	ds_write_b128 v158, v[74:77] offset:9216
	ds_write_b128 v158, v[78:81] offset:10368
	s_waitcnt lgkmcnt(0)
	s_barrier
	s_cmp_eq_u32 s5, 1
	s_cbranch_scc0 .Lat1_kb3_end
	ds_read_b128 v[18:21], v8 offset:0
	ds_read_b128 v[22:25], v8 offset:64
	ds_read_b128 v[26:29], v8 offset:2304
	ds_read_b128 v[30:33], v8 offset:2368
	ds_read_b128 v[34:37], v8 offset:4608
	ds_read_b128 v[38:41], v8 offset:4672
	ds_read_b128 v[42:45], v8 offset:6912
	ds_read_b128 v[46:49], v8 offset:6976
	ds_read_b64_tr_b16 v[216:217], v159
	ds_read_b64_tr_b16 v[218:219], v159 offset:2304
	ds_read_b64_tr_b16 v[220:221], v159 offset:4608
	ds_read_b64_tr_b16 v[222:223], v159 offset:6912
	ds_read_b64_tr_b16 v[224:225], v159 offset:32
	ds_read_b64_tr_b16 v[226:227], v159 offset:2336
	ds_read_b64_tr_b16 v[228:229], v159 offset:4640
	ds_read_b64_tr_b16 v[230:231], v159 offset:6944
	ds_read_b64_tr_b16 v[232:233], v159 offset:64
	ds_read_b64_tr_b16 v[234:235], v159 offset:2368
	ds_read_b64_tr_b16 v[236:237], v159 offset:4672
	ds_read_b64_tr_b16 v[238:239], v159 offset:6976
	ds_read_b64_tr_b16 v[240:241], v159 offset:96
	ds_read_b64_tr_b16 v[242:243], v159 offset:2400
	ds_read_b64_tr_b16 v[244:245], v159 offset:4704
	ds_read_b64_tr_b16 v[246:247], v159 offset:7008
	s_waitcnt lgkmcnt(15)
	v_mfma_f32_16x16x32_f16 v[114:117], v[18:21], v[10:13], 0
	v_mfma_f32_16x16x32_f16 v[118:121], v[26:29], v[10:13], 0
	v_mfma_f32_16x16x32_f16 v[122:125], v[34:37], v[10:13], 0
	v_mfma_f32_16x16x32_f16 v[126:129], v[42:45], v[10:13], 0
	v_mfma_f32_16x16x32_f16 v[114:117], v[22:25], v[14:17], v[114:117]
	v_mfma_f32_16x16x32_f16 v[118:121], v[30:33], v[14:17], v[118:121]
	v_mfma_f32_16x16x32_f16 v[122:125], v[38:41], v[14:17], v[122:125]
	v_mfma_f32_16x16x32_f16 v[126:129], v[46:49], v[14:17], v[126:129]
	s_nop 7
	s_nop 7
	v_mul_f32_e32 v114, 0x3e000000, v114
	v_mul_f32_e32 v115, 0x3e000000, v115
	v_mul_f32_e32 v116, 0x3e000000, v116
	v_mul_f32_e32 v117, 0x3e000000, v117
	v_mul_f32_e32 v118, 0x3e000000, v118
	v_mul_f32_e32 v119, 0x3e000000, v119
	v_mul_f32_e32 v120, 0x3e000000, v120
	v_mul_f32_e32 v121, 0x3e000000, v121
	v_mul_f32_e32 v122, 0x3e000000, v122
	v_mul_f32_e32 v123, 0x3e000000, v123
	v_mul_f32_e32 v124, 0x3e000000, v124
	v_mul_f32_e32 v125, 0x3e000000, v125
	v_mul_f32_e32 v126, 0x3e000000, v126
	v_mul_f32_e32 v127, 0x3e000000, v127
	v_mul_f32_e32 v128, 0x3e000000, v128
	v_mul_f32_e32 v129, 0x3e000000, v129
	v_max3_f32 v179, v114, v115, v116
	v_max3_f32 v179, v179, v117, v118
	v_max3_f32 v179, v179, v119, v120
	v_max3_f32 v179, v179, v121, v122
	v_max3_f32 v179, v179, v123, v124
	v_max3_f32 v179, v179, v125, v126
	v_max3_f32 v179, v179, v127, v128
	v_max_f32_e32 v179, v179, v129
	v_mov_b32_e32 v201, v179
	s_nop 1
	v_permlane16_swap_b32 v201, v179
	s_nop 1
	v_max_f32_e32 v179, v179, v201
	v_mov_b32_e32 v201, v179
	s_nop 1
	v_permlane32_swap_b32 v201, v179
	s_nop 1
	v_max3_f32 v179, v179, v201, v176
	v_sub_f32_e32 v178, v176, v179
	v_mul_f32_e32 v178, 0x3fb8aa3b, v178
	v_exp_f32_e32 v178, v178
	v_mov_b32_e32 v176, v179
	v_mul_f32_e32 v202, 0xbfb8aa3b, v179
	v_mov_b32_e32 v203, 0x3fb8aa3b
	v_fma_f32 v114, v114, v203, v202
	v_fma_f32 v115, v115, v203, v202
	v_fma_f32 v116, v116, v203, v202
	v_fma_f32 v117, v117, v203, v202
	v_fma_f32 v118, v118, v203, v202
	v_fma_f32 v119, v119, v203, v202
	v_fma_f32 v120, v120, v203, v202
	v_fma_f32 v121, v121, v203, v202
	v_fma_f32 v122, v122, v203, v202
	v_fma_f32 v123, v123, v203, v202
	v_fma_f32 v124, v124, v203, v202
	v_fma_f32 v125, v125, v203, v202
	v_fma_f32 v126, v126, v203, v202
	v_fma_f32 v127, v127, v203, v202
	v_fma_f32 v128, v128, v203, v202
	v_fma_f32 v129, v129, v203, v202
	v_exp_f32_e32 v114, v114
	v_exp_f32_e32 v115, v115
	v_exp_f32_e32 v116, v116
	v_exp_f32_e32 v117, v117
	v_exp_f32_e32 v118, v118
	v_exp_f32_e32 v119, v119
	v_exp_f32_e32 v120, v120
	v_exp_f32_e32 v121, v121
	v_exp_f32_e32 v122, v122
	v_exp_f32_e32 v123, v123
	v_exp_f32_e32 v124, v124
	v_exp_f32_e32 v125, v125
	v_exp_f32_e32 v126, v126
	v_exp_f32_e32 v127, v127
	v_exp_f32_e32 v128, v128
	v_exp_f32_e32 v129, v129
	s_nop 0
	v_fma_f32 v177, v177, v178, v114
	v_add_f32_e32 v177, v177, v115
	v_add_f32_e32 v177, v177, v116
	v_add_f32_e32 v177, v177, v117
	v_add_f32_e32 v177, v177, v118
	v_add_f32_e32 v177, v177, v119
	v_add_f32_e32 v177, v177, v120
	v_add_f32_e32 v177, v177, v121
	v_add_f32_e32 v177, v177, v122
	v_add_f32_e32 v177, v177, v123
	v_add_f32_e32 v177, v177, v124
	v_add_f32_e32 v177, v177, v125
	v_add_f32_e32 v177, v177, v126
	v_add_f32_e32 v177, v177, v127
	v_add_f32_e32 v177, v177, v128
	v_add_f32_e32 v177, v177, v129
	v_cvt_pk_f16_f32 v130, v114, v115
	v_cvt_pk_f16_f32 v131, v116, v117
	v_cvt_pk_f16_f32 v132, v118, v119
	v_cvt_pk_f16_f32 v133, v120, v121
	v_cvt_pk_f16_f32 v134, v122, v123
	v_cvt_pk_f16_f32 v135, v124, v125
	v_cvt_pk_f16_f32 v136, v126, v127
	v_cvt_pk_f16_f32 v137, v128, v129
	v_pk_mul_f32 v[138:139], v[138:139], v[178:179] op_sel_hi:[1,0]
	v_pk_mul_f32 v[140:141], v[140:141], v[178:179] op_sel_hi:[1,0]
	v_pk_mul_f32 v[142:143], v[142:143], v[178:179] op_sel_hi:[1,0]
	v_pk_mul_f32 v[144:145], v[144:145], v[178:179] op_sel_hi:[1,0]
	v_pk_mul_f32 v[146:147], v[146:147], v[178:179] op_sel_hi:[1,0]
	v_pk_mul_f32 v[148:149], v[148:149], v[178:179] op_sel_hi:[1,0]
	v_pk_mul_f32 v[150:151], v[150:151], v[178:179] op_sel_hi:[1,0]
	v_pk_mul_f32 v[152:153], v[152:153], v[178:179] op_sel_hi:[1,0]
	s_waitcnt lgkmcnt(0)
	s_nop 1
	v_mfma_f32_16x16x32_f16 v[138:141], v[216:219], v[130:133], v[138:141]
	v_mfma_f32_16x16x32_f16 v[142:145], v[224:227], v[130:133], v[142:145]
	v_mfma_f32_16x16x32_f16 v[146:149], v[232:235], v[130:133], v[146:149]
	v_mfma_f32_16x16x32_f16 v[150:153], v[240:243], v[130:133], v[150:153]
	v_mfma_f32_16x16x32_f16 v[138:141], v[220:223], v[134:137], v[138:141]
	v_mfma_f32_16x16x32_f16 v[142:145], v[228:231], v[134:137], v[142:145]
	v_mfma_f32_16x16x32_f16 v[146:149], v[236:239], v[134:137], v[146:149]
	v_mfma_f32_16x16x32_f16 v[150:153], v[244:247], v[134:137], v[150:153]
; DI float grp16_sum(float v) { v += __shfl_xor(v, 1); v += __shfl_xor(v, 2); v += __shfl_xor(v, 4); v += __shfl_xor(v, 8); return v; }
; DI float grp16_max(float v) { v = fmaxf(v, __shfl_xor(v, 1)); v = fmaxf(v, __shfl_xor(v, 2)); v = fmaxf(v, __shfl_xor(v, 4)); v = fmaxf(v, __shfl_xor(v, 8)); return v; }
; template <int NKB>
; DI void attn_unit(const Params& p, int l, int mode, int grp, int head, int r0, int dil, int i0, int sub_len, int W, h16* lds) {
;     ...
;   for (int kb = 0; kb < NKB; ++kb) {
;     const int j0 = i0 - W + 64 * kb;
;     const bool inr = (j0 >= 0) && (j0 < sub_len);
;     __syncthreads();
;     img_store_nat(Ki, lrow, seg, pk0, pk1);
;     img_store_T(Vt, lrow, seg, pv0, pv1);
;     __syncthreads();
;     if (kb + 1 < NKB) ATT_PREFETCH(kb + 1);
;     f4v S[4];
; #pragma unroll
;     for (int i = 0; i < 4; ++i) S[i] = (f4v){0.f, 0.f, 0.f, 0.f};
;     mm64(Qi, Ki, S, w, lane);
;     float mx[4], al[4], rsum[4];
;     bool vm[4][4];
; #pragma unroll
;     for (int rg = 0; rg < 4; ++rg) {
;       const int row = 16 * w + 4 * q + rg;
;       float m_ = -1e30f;
; #pragma unroll
;       for (int nt = 0; nt < 4; ++nt) {
;         const int key = 16 * nt + r;
;         const int delta = row - key + W - 64 * kb;
;         const bool ok = inr && (delta >= -W) && (delta <= W);
;         vm[nt][rg] = ok;
;         float s = S[nt][rg] * 0.125f;
;         S[nt][rg] = s;
;         if (ok) m_ = fmaxf(m_, s);
;       }
;       mx[rg] = grp16_max(m_);
;     }
; #pragma unroll
;     for (int rg = 0; rg < 4; ++rg) {
;       const float mn = fmaxf(mrow[rg], mx[rg]);
;       al[rg] = __expf(mrow[rg] - mn);
;       mrow[rg] = mn;
;       float rs_ = 0.f;
; #pragma unroll
;       for (int nt = 0; nt < 4; ++nt) {
;         float pv = vm[nt][rg] ? __expf(S[nt][rg] - mn) : 0.f;
;         rs_ += pv;
;         Pi[(16 * w + 4 * q + rg) * LDH + 16 * nt + r] = (h16)pv;
;       }
;       rsum[rg] = grp16_sum(rs_);
;       lsum[rg] = lsum[rg] * al[rg] + rsum[rg];
;     }
; #pragma unroll
;     for (int et = 0; et < 4; ++et)
; #pragma unroll
;       for (int rg = 0; rg < 4; ++rg) O[et][rg] *= al[rg];
.Lat1_kb3_end:
	s_waitcnt vmcnt(0)
	ds_write_b128 v158, v[50:53] offset:18432
	ds_write_b128 v158, v[54:57] offset:19584
	ds_write_b128 v158, v[58:61] offset:27648
	ds_write_b128 v158, v[62:65] offset:28800
	s_waitcnt lgkmcnt(0)
	s_barrier
	s_cmp_eq_u32 s6, 1
	s_cbranch_scc0 .Lat1_kb4_end
	ds_read_b128 v[18:21], v8 offset:18432
	ds_read_b128 v[22:25], v8 offset:18496
	ds_read_b128 v[26:29], v8 offset:20736
	ds_read_b128 v[30:33], v8 offset:20800
	ds_read_b128 v[34:37], v8 offset:23040
	ds_read_b128 v[38:41], v8 offset:23104
	ds_read_b128 v[42:45], v8 offset:25344
	ds_read_b128 v[46:49], v8 offset:25408
	ds_read_b64_tr_b16 v[216:217], v159 offset:18432
	ds_read_b64_tr_b16 v[218:219], v159 offset:20736
	ds_read_b64_tr_b16 v[220:221], v159 offset:23040
	ds_read_b64_tr_b16 v[222:223], v159 offset:25344
	ds_read_b64_tr_b16 v[224:225], v159 offset:18464
	ds_read_b64_tr_b16 v[226:227], v159 offset:20768
	ds_read_b64_tr_b16 v[228:229], v159 offset:23072
	ds_read_b64_tr_b16 v[230:231], v159 offset:25376
	ds_read_b64_tr_b16 v[232:233], v159 offset:18496
	ds_read_b64_tr_b16 v[234:235], v159 offset:20800
	ds_read_b64_tr_b16 v[236:237], v159 offset:23104
	ds_read_b64_tr_b16 v[238:239], v159 offset:25408
	ds_read_b64_tr_b16 v[240:241], v159 offset:18528
	ds_read_b64_tr_b16 v[242:243], v159 offset:20832
	ds_read_b64_tr_b16 v[244:245], v159 offset:23136
	ds_read_b64_tr_b16 v[246:247], v159 offset:25440
	s_waitcnt lgkmcnt(15)
	v_mfma_f32_16x16x32_f16 v[114:117], v[18:21], v[10:13], 0
	v_mfma_f32_16x16x32_f16 v[118:121], v[26:29], v[10:13], 0
	v_mfma_f32_16x16x32_f16 v[122:125], v[34:37], v[10:13], 0
	v_mfma_f32_16x16x32_f16 v[126:129], v[42:45], v[10:13], 0
	v_mfma_f32_16x16x32_f16 v[114:117], v[22:25], v[14:17], v[114:117]
	v_mfma_f32_16x16x32_f16 v[118:121], v[30:33], v[14:17], v[118:121]
	v_mfma_f32_16x16x32_f16 v[122:125], v[38:41], v[14:17], v[122:125]
	v_mfma_f32_16x16x32_f16 v[126:129], v[46:49], v[14:17], v[126:129]
	s_nop 7
	s_nop 7
	v_mul_f32_e32 v114, 0x3e000000, v114
	v_mul_f32_e32 v115, 0x3e000000, v115
	v_mul_f32_e32 v116, 0x3e000000, v116
	v_mul_f32_e32 v117, 0x3e000000, v117
	v_mul_f32_e32 v118, 0x3e000000, v118
	v_mul_f32_e32 v119, 0x3e000000, v119
	v_mul_f32_e32 v120, 0x3e000000, v120
	v_mul_f32_e32 v121, 0x3e000000, v121
	v_mul_f32_e32 v122, 0x3e000000, v122
	v_mul_f32_e32 v123, 0x3e000000, v123
	v_mul_f32_e32 v124, 0x3e000000, v124
	v_mul_f32_e32 v125, 0x3e000000, v125
	v_mul_f32_e32 v126, 0x3e000000, v126
	v_mul_f32_e32 v127, 0x3e000000, v127
	v_mul_f32_e32 v128, 0x3e000000, v128
	v_mul_f32_e32 v129, 0x3e000000, v129
	v_mov_b32_e32 v200, 0xf149f2ca
	v_cmp_ge_i32_e32 vcc, 0, v160
	v_cndmask_b32_e32 v114, v200, v114, vcc
	v_cmp_ge_i32_e32 vcc, -1, v160
	v_cndmask_b32_e32 v115, v200, v115, vcc
	v_cmp_ge_i32_e32 vcc, -2, v160
	v_cndmask_b32_e32 v116, v200, v116, vcc
	v_cmp_ge_i32_e32 vcc, -3, v160
	v_cndmask_b32_e32 v117, v200, v117, vcc
	v_cmp_ge_i32_e32 vcc, -16, v160
	v_cndmask_b32_e32 v118, v200, v118, vcc
	v_cmp_ge_i32_e32 vcc, -17, v160
	v_cndmask_b32_e32 v119, v200, v119, vcc
	v_cmp_ge_i32_e32 vcc, -18, v160
	v_cndmask_b32_e32 v120, v200, v120, vcc
	v_cmp_ge_i32_e32 vcc, -19, v160
	v_cndmask_b32_e32 v121, v200, v121, vcc
	v_cmp_ge_i32_e32 vcc, -32, v160
	v_cndmask_b32_e32 v122, v200, v122, vcc
	v_cmp_ge_i32_e32 vcc, -33, v160
	v_cndmask_b32_e32 v123, v200, v123, vcc
	v_cmp_ge_i32_e32 vcc, -34, v160
	v_cndmask_b32_e32 v124, v200, v124, vcc
	v_cmp_ge_i32_e32 vcc, -35, v160
	v_cndmask_b32_e32 v125, v200, v125, vcc
	v_cmp_ge_i32_e32 vcc, -48, v160
	v_cndmask_b32_e32 v126, v200, v126, vcc
	v_cmp_ge_i32_e32 vcc, -49, v160
	v_cndmask_b32_e32 v127, v200, v127, vcc
	v_cmp_ge_i32_e32 vcc, -50, v160
	v_cndmask_b32_e32 v128, v200, v128, vcc
	v_cmp_ge_i32_e32 vcc, -51, v160
	v_cndmask_b32_e32 v129, v200, v129, vcc
	v_max3_f32 v179, v114, v115, v116
	v_max3_f32 v179, v179, v117, v118
	v_max3_f32 v179, v179, v119, v120
	v_max3_f32 v179, v179, v121, v122
	v_max3_f32 v179, v179, v123, v124
	v_max3_f32 v179, v179, v125, v126
	v_max3_f32 v179, v179, v127, v128
	v_max_f32_e32 v179, v179, v129
	v_mov_b32_e32 v201, v179
	s_nop 1
	v_permlane16_swap_b32 v201, v179
	s_nop 1
	v_max_f32_e32 v179, v179, v201
	v_mov_b32_e32 v201, v179
	s_nop 1
	v_permlane32_swap_b32 v201, v179
	s_nop 1
	v_max3_f32 v179, v179, v201, v176
	v_sub_f32_e32 v178, v176, v179
	v_mul_f32_e32 v178, 0x3fb8aa3b, v178
	v_exp_f32_e32 v178, v178
	v_mov_b32_e32 v176, v179
	v_mul_f32_e32 v202, 0xbfb8aa3b, v179
	v_mov_b32_e32 v203, 0x3fb8aa3b
	v_fma_f32 v114, v114, v203, v202
	v_fma_f32 v115, v115, v203, v202
	v_fma_f32 v116, v116, v203, v202
	v_fma_f32 v117, v117, v203, v202
	v_fma_f32 v118, v118, v203, v202
	v_fma_f32 v119, v119, v203, v202
	v_fma_f32 v120, v120, v203, v202
	v_fma_f32 v121, v121, v203, v202
	v_fma_f32 v122, v122, v203, v202
	v_fma_f32 v123, v123, v203, v202
	v_fma_f32 v124, v124, v203, v202
	v_fma_f32 v125, v125, v203, v202
	v_fma_f32 v126, v126, v203, v202
	v_fma_f32 v127, v127, v203, v202
	v_fma_f32 v128, v128, v203, v202
	v_fma_f32 v129, v129, v203, v202
	v_exp_f32_e32 v114, v114
	v_exp_f32_e32 v115, v115
	v_exp_f32_e32 v116, v116
	v_exp_f32_e32 v117, v117
	v_exp_f32_e32 v118, v118
	v_exp_f32_e32 v119, v119
	v_exp_f32_e32 v120, v120
	v_exp_f32_e32 v121, v121
	v_exp_f32_e32 v122, v122
	v_exp_f32_e32 v123, v123
	v_exp_f32_e32 v124, v124
	v_exp_f32_e32 v125, v125
	v_exp_f32_e32 v126, v126
	v_exp_f32_e32 v127, v127
	v_exp_f32_e32 v128, v128
	v_exp_f32_e32 v129, v129
	s_nop 0
	v_fma_f32 v177, v177, v178, v114
	v_add_f32_e32 v177, v177, v115
	v_add_f32_e32 v177, v177, v116
	v_add_f32_e32 v177, v177, v117
	v_add_f32_e32 v177, v177, v118
	v_add_f32_e32 v177, v177, v119
	v_add_f32_e32 v177, v177, v120
	v_add_f32_e32 v177, v177, v121
	v_add_f32_e32 v177, v177, v122
	v_add_f32_e32 v177, v177, v123
	v_add_f32_e32 v177, v177, v124
	v_add_f32_e32 v177, v177, v125
	v_add_f32_e32 v177, v177, v126
	v_add_f32_e32 v177, v177, v127
	v_add_f32_e32 v177, v177, v128
	v_add_f32_e32 v177, v177, v129
	v_cvt_pk_f16_f32 v130, v114, v115
	v_cvt_pk_f16_f32 v131, v116, v117
	v_cvt_pk_f16_f32 v132, v118, v119
	v_cvt_pk_f16_f32 v133, v120, v121
	v_cvt_pk_f16_f32 v134, v122, v123
	v_cvt_pk_f16_f32 v135, v124, v125
	v_cvt_pk_f16_f32 v136, v126, v127
	v_cvt_pk_f16_f32 v137, v128, v129
	v_pk_mul_f32 v[138:139], v[138:139], v[178:179] op_sel_hi:[1,0]
	v_pk_mul_f32 v[140:141], v[140:141], v[178:179] op_sel_hi:[1,0]
	v_pk_mul_f32 v[142:143], v[142:143], v[178:179] op_sel_hi:[1,0]
	v_pk_mul_f32 v[144:145], v[144:145], v[178:179] op_sel_hi:[1,0]
	v_pk_mul_f32 v[146:147], v[146:147], v[178:179] op_sel_hi:[1,0]
	v_pk_mul_f32 v[148:149], v[148:149], v[178:179] op_sel_hi:[1,0]
	v_pk_mul_f32 v[150:151], v[150:151], v[178:179] op_sel_hi:[1,0]
	v_pk_mul_f32 v[152:153], v[152:153], v[178:179] op_sel_hi:[1,0]
	s_waitcnt lgkmcnt(0)
; template <int NKB>
; DI void attn_unit(const Params& p, int l, int mode, int grp, int head, int r0, int dil, int i0, int sub_len, int W, h16* lds) {
;     ...
;     mm64(Pi, Vt, O, w, lane);
;   }
; #pragma unroll
;   for (int rg = 0; rg < 4; ++rg) {
;     const int row = 16 * w + 4 * q + rg;
;     const size_t pos = (size_t)r0 + (size_t)dil * (i0 + row);
;     const float inv = 1.f / lsum[rg];
;     if (mode == 0) {
;       h16* ob = (h16*)(ws + OFF_OB) + ((size_t)grp * SEQ + pos) * 256 + head * 64;
; #pragma unroll
;       for (int et = 0; et < 4; ++et) ob[16 * et + r] = (h16)(O[et][rg] * inv);
;       if (r == 0) {
;         float* ml = (float*)(ws + OFF_MLB) + (((size_t)grp * SEQ + pos) * 4 + head) * 2;
;         ml[0] = mrow[rg]; ml[1] = lsum[rg];
;       }
;     } else {
;       h16* y = (h16*)(ws + OFF_Y) + pos * 1280 + 768 + head * 64;
; #pragma unroll
;       for (int et = 0; et < 4; ++et) y[16 * et + r] = (h16)(O[et][rg] * inv);
	s_nop 1
	v_mfma_f32_16x16x32_f16 v[138:141], v[216:219], v[130:133], v[138:141]
	v_mfma_f32_16x16x32_f16 v[142:145], v[224:227], v[130:133], v[142:145]
	v_mfma_f32_16x16x32_f16 v[146:149], v[232:235], v[130:133], v[146:149]
	v_mfma_f32_16x16x32_f16 v[150:153], v[240:243], v[130:133], v[150:153]
	v_mfma_f32_16x16x32_f16 v[138:141], v[220:223], v[134:137], v[138:141]
	v_mfma_f32_16x16x32_f16 v[142:145], v[228:231], v[134:137], v[142:145]
	v_mfma_f32_16x16x32_f16 v[146:149], v[236:239], v[134:137], v[146:149]
	v_mfma_f32_16x16x32_f16 v[150:153], v[244:247], v[134:137], v[150:153]
.Lat1_kb4_end:
	s_nop 7
	s_nop 1
	v_mov_b32_e32 v201, v177
	s_nop 1
	v_permlane16_swap_b32 v201, v177
	s_nop 1
	v_add_f32_e32 v177, v177, v201
	v_mov_b32_e32 v201, v177
	s_nop 1
	v_permlane32_swap_b32 v201, v177
	s_nop 1
	v_add_f32_e32 v177, v177, v201
	v_rcp_f32_e32 v178, v177
	s_nop 0
	v_pk_mul_f32 v[138:139], v[138:139], v[178:179] op_sel_hi:[1,0]
	v_pk_mul_f32 v[140:141], v[140:141], v[178:179] op_sel_hi:[1,0]
	v_pk_mul_f32 v[142:143], v[142:143], v[178:179] op_sel_hi:[1,0]
	v_pk_mul_f32 v[144:145], v[144:145], v[178:179] op_sel_hi:[1,0]
	v_pk_mul_f32 v[146:147], v[146:147], v[178:179] op_sel_hi:[1,0]
	v_pk_mul_f32 v[148:149], v[148:149], v[178:179] op_sel_hi:[1,0]
	v_pk_mul_f32 v[150:151], v[150:151], v[178:179] op_sel_hi:[1,0]
	v_pk_mul_f32 v[152:153], v[152:153], v[178:179] op_sel_hi:[1,0]
	v_cvt_pk_f16_f32 v130, v138, v139
	v_cvt_pk_f16_f32 v131, v140, v141
	v_cvt_pk_f16_f32 v132, v142, v143
	v_cvt_pk_f16_f32 v133, v144, v145
	v_cvt_pk_f16_f32 v134, v146, v147
	v_cvt_pk_f16_f32 v135, v148, v149
	v_cvt_pk_f16_f32 v136, v150, v151
	v_cvt_pk_f16_f32 v137, v152, v153
	global_store_dwordx2 v249, v[130:131], s[48:49]
	global_store_dwordx2 v249, v[132:133], s[48:49] offset:32
	global_store_dwordx2 v249, v[134:135], s[48:49] offset:64
	global_store_dwordx2 v249, v[136:137], s[48:49] offset:96
